# plus: DeltaNet forward-substitution rank-16 updates use v_pk_fma_f32 on register pairs (same FMAs, same order), on top of the previous version
# baseline (speedup 1.0000x reference)
.LBB0_809:
	v_readlane_b32 s6, v253, 34
	s_waitcnt lgkmcnt(0)
	s_barrier
	v_mov_b32_e32 v5, s6
	ds_read_b128 v[178:181], v5 offset:18688
	ds_read_b128 v[182:185], v5 offset:18944
	ds_read_b128 v[186:189], v5 offset:19200
	ds_read_b128 v[190:193], v5 offset:19456
	ds_read_b128 v[194:197], v5 offset:19712
	ds_read_b128 v[198:201], v5 offset:19728
	ds_read_b128 v[202:205], v5 offset:19968
	ds_read_b128 v[206:209], v5 offset:19984
	ds_read_b128 v[214:217], v5 offset:20224
	ds_read_b128 v[228:231], v5 offset:20240
	s_waitcnt lgkmcnt(9)
	v_fma_f32 v0, -v60, v178, v61
	v_fma_f32 v0, -v61, v179, v0
	v_fma_f32 v0, -v82, v180, v0
	v_fma_f32 v0, -v83, v181, v0
	ds_read_b128 v[232:235], v5 offset:20480
	s_waitcnt lgkmcnt(9)
	v_fma_f32 v1, -v60, v182, v82
	v_fma_f32 v1, -v183, v0, v1
	v_fma_f32 v1, -v82, v184, v1
	v_fma_f32 v1, -v83, v185, v1
	ds_read_b128 v[244:247], v5 offset:20496
	s_waitcnt lgkmcnt(9)
	v_fma_f32 v2, -v60, v186, v83
	v_fma_f32 v2, -v187, v0, v2
	v_fma_f32 v2, -v188, v1, v2
	v_fma_f32 v2, -v83, v189, v2
	ds_read_b128 v[178:181], v5 offset:20736
	s_waitcnt lgkmcnt(9)
	v_fma_f32 v3, -v60, v190, v86
	v_fma_f32 v3, -v191, v0, v3
	v_fma_f32 v3, -v192, v1, v3
	v_fma_f32 v3, -v193, v2, v3
	ds_read_b128 v[182:185], v5 offset:20752
	s_waitcnt lgkmcnt(9)
	v_fma_f32 v4, -v60, v194, v87
	v_fma_f32 v4, -v195, v0, v4
	v_fma_f32 v4, -v196, v1, v4
	v_fma_f32 v4, -v197, v2, v4
	ds_read_b128 v[186:189], v5 offset:20768
	s_waitcnt lgkmcnt(9)
	v_fma_f32 v4, -v198, v3, v4
	v_fma_f32 v4, -v87, v199, v4
	v_fma_f32 v4, -v80, v200, v4
	v_fma_f32 v4, -v81, v201, v4
	ds_read_b128 v[190:193], v5 offset:20992
	s_waitcnt lgkmcnt(9)
	v_fma_f32 v6, -v60, v202, v80
	v_fma_f32 v6, -v0, v203, v6
	v_fma_f32 v6, -v204, v1, v6
	v_fma_f32 v10, -v205, v2, v6
	ds_read_b128 v[194:197], v5 offset:21008
	s_waitcnt lgkmcnt(9)
	v_fma_f32 v6, -v206, v3, v10
	v_fma_f32 v6, -v207, v4, v6
	v_fma_f32 v6, -v80, v208, v6
	v_fma_f32 v6, -v81, v209, v6
	ds_read_b128 v[198:201], v5 offset:21024
	s_waitcnt lgkmcnt(9)
	v_fma_f32 v7, -v60, v214, v81
	v_fma_f32 v7, -v0, v215, v7
	v_fma_f32 v7, -v216, v1, v7
	v_fma_f32 v7, -v217, v2, v7
	ds_read_b128 v[202:205], v5 offset:21248
	s_waitcnt lgkmcnt(9)
	v_fma_f32 v7, -v228, v3, v7
	v_fma_f32 v7, -v229, v4, v7
	v_fma_f32 v7, -v230, v6, v7
	v_fma_f32 v7, -v81, v231, v7
	ds_read_b128 v[206:209], v5 offset:21264
	s_waitcnt lgkmcnt(9)
	v_fma_f32 v8, -v60, v232, v72
	v_fma_f32 v8, -v0, v233, v8
	v_fma_f32 v8, -v1, v234, v8
	v_fma_f32 v12, -v235, v2, v8
	ds_read_b128 v[214:217], v5 offset:21280
	s_waitcnt lgkmcnt(9)
	v_fma_f32 v8, -v244, v3, v12
	v_fma_f32 v8, -v245, v4, v8
	v_fma_f32 v8, -v246, v6, v8
	v_fma_f32 v8, -v247, v7, v8
	ds_read_b128 v[228:231], v5 offset:21504
	s_waitcnt lgkmcnt(9)
	v_fma_f32 v9, -v60, v178, v73
	v_fma_f32 v9, -v0, v179, v9
	v_fma_f32 v9, -v1, v180, v9
	v_fma_f32 v9, -v181, v2, v9
	ds_read_b128 v[232:235], v5 offset:21520
	s_waitcnt lgkmcnt(9)
	v_fma_f32 v9, -v182, v3, v9
	v_fma_f32 v9, -v183, v4, v9
	v_fma_f32 v9, -v184, v6, v9
	v_fma_f32 v9, -v185, v7, v9
	ds_read_b128 v[244:247], v5 offset:21536
	s_waitcnt lgkmcnt(9)
	v_fma_f32 v9, -v186, v8, v9
	v_fma_f32 v9, -v73, v187, v9
	v_fma_f32 v9, -v54, v188, v9
	v_fma_f32 v9, -v55, v189, v9
	ds_read_b128 v[178:181], v5 offset:21760
	s_waitcnt lgkmcnt(9)
	v_fma_f32 v10, -v60, v190, v54
	v_fma_f32 v10, -v0, v191, v10
	v_fma_f32 v10, -v1, v192, v10
	v_fma_f32 v14, -v2, v193, v10
	ds_read_b128 v[182:185], v5 offset:21776
	s_waitcnt lgkmcnt(9)
	v_fma_f32 v10, -v3, v194, v14
	v_fma_f32 v10, -v195, v4, v10
	v_fma_f32 v10, -v196, v6, v10
	v_fma_f32 v14, -v197, v7, v10
	ds_read_b128 v[186:189], v5 offset:21792
	s_waitcnt lgkmcnt(9)
	v_fma_f32 v10, -v198, v8, v14
	v_fma_f32 v10, -v199, v9, v10
	v_fma_f32 v10, -v54, v200, v10
	v_fma_f32 v10, -v55, v201, v10
	ds_read_b128 v[190:193], v5 offset:21808
	s_waitcnt lgkmcnt(9)
	v_fma_f32 v11, -v60, v202, v55
	v_fma_f32 v11, -v0, v203, v11
	v_fma_f32 v11, -v1, v204, v11
	v_fma_f32 v11, -v2, v205, v11
	ds_read_b128 v[194:197], v5 offset:22016
	s_waitcnt lgkmcnt(9)
	v_fma_f32 v11, -v3, v206, v11
	v_fma_f32 v11, -v207, v4, v11
	v_fma_f32 v11, -v208, v6, v11
	v_fma_f32 v11, -v209, v7, v11
	ds_read_b128 v[198:201], v5 offset:22032
	s_waitcnt lgkmcnt(9)
	v_fma_f32 v11, -v214, v8, v11
	v_fma_f32 v11, -v215, v9, v11
	v_fma_f32 v11, -v216, v10, v11
	v_fma_f32 v11, -v55, v217, v11
	ds_read_b128 v[202:205], v5 offset:22048
	s_waitcnt lgkmcnt(9)
	v_fma_f32 v12, -v60, v228, v52
	v_fma_f32 v12, -v0, v229, v12
	v_fma_f32 v12, -v1, v230, v12
	v_fma_f32 v16, -v2, v231, v12
	ds_read_b128 v[206:209], v5 offset:22064
	s_waitcnt lgkmcnt(9)
	v_fma_f32 v12, -v3, v232, v16
	v_fma_f32 v12, -v4, v233, v12
	v_fma_f32 v12, -v234, v6, v12
	v_fma_f32 v16, -v235, v7, v12
	ds_read_b128 v[214:217], v5 offset:22272
	s_waitcnt lgkmcnt(9)
	v_fma_f32 v12, -v244, v8, v16
	v_fma_f32 v12, -v245, v9, v12
	v_fma_f32 v12, -v246, v10, v12
	v_fma_f32 v12, -v247, v11, v12
	ds_read_b128 v[228:231], v5 offset:22288
	s_waitcnt lgkmcnt(9)
	v_fma_f32 v13, -v60, v178, v53
	v_fma_f32 v13, -v0, v179, v13
	v_fma_f32 v13, -v1, v180, v13
	v_fma_f32 v13, -v2, v181, v13
	ds_read_b128 v[232:235], v5 offset:22304
	s_waitcnt lgkmcnt(9)
	v_fma_f32 v13, -v3, v182, v13
	v_fma_f32 v13, -v4, v183, v13
	v_fma_f32 v13, -v6, v184, v13
	v_fma_f32 v13, -v185, v7, v13
	ds_read_b128 v[244:247], v5 offset:22320
	s_waitcnt lgkmcnt(9)
	v_fma_f32 v13, -v186, v8, v13
	v_fma_f32 v13, -v187, v9, v13
	v_fma_f32 v13, -v188, v10, v13
	v_fma_f32 v13, -v189, v11, v13
	ds_read_b128 v[178:181], v5 offset:22528
	s_waitcnt lgkmcnt(9)
	v_fma_f32 v13, -v190, v12, v13
	v_fma_f32 v13, -v53, v191, v13
	v_fma_f32 v13, -v50, v192, v13
	v_fma_f32 v13, -v51, v193, v13
	ds_read_b128 v[182:185], v5 offset:22544
	s_waitcnt lgkmcnt(9)
	v_fma_f32 v14, -v60, v194, v50
	v_fma_f32 v14, -v0, v195, v14
	v_fma_f32 v14, -v1, v196, v14
	v_fma_f32 v18, -v2, v197, v14
	ds_read_b128 v[186:189], v5 offset:22560
	s_waitcnt lgkmcnt(9)
	v_fma_f32 v14, -v3, v198, v18
	v_fma_f32 v14, -v4, v199, v14
	v_fma_f32 v14, -v6, v200, v14
	v_fma_f32 v18, -v7, v201, v14
	ds_read_b128 v[190:193], v5 offset:22576
	s_waitcnt lgkmcnt(9)
	v_fma_f32 v14, -v8, v202, v18
	v_fma_f32 v14, -v203, v9, v14
	v_fma_f32 v14, -v204, v10, v14
	v_fma_f32 v18, -v205, v11, v14
	ds_read_b128 v[194:197], v5 offset:22800
	s_waitcnt lgkmcnt(9)
	v_fma_f32 v14, -v206, v12, v18
	v_fma_f32 v14, -v207, v13, v14
	v_fma_f32 v14, -v50, v208, v14
	v_fma_f32 v14, -v51, v209, v14
	ds_read_b128 v[198:201], v5 offset:22784
	s_waitcnt lgkmcnt(9)
	v_fma_f32 v15, -v60, v214, v51
	v_fma_f32 v15, -v0, v215, v15
	v_fma_f32 v15, -v1, v216, v15
	v_fma_f32 v15, -v2, v217, v15
	ds_read_b128 v[202:205], v5 offset:22832
	s_waitcnt lgkmcnt(9)
	v_fma_f32 v15, -v3, v228, v15
	v_fma_f32 v15, -v4, v229, v15
	v_fma_f32 v15, -v6, v230, v15
	v_fma_f32 v15, -v7, v231, v15
	ds_read_b128 v[206:209], v5 offset:22816
	s_waitcnt lgkmcnt(9)
	v_fma_f32 v15, -v8, v232, v15
	v_fma_f32 v15, -v9, v233, v15
	v_fma_f32 v15, -v234, v10, v15
	v_fma_f32 v15, -v235, v11, v15
	ds_read_b128 v[214:217], v5 offset:23040
	s_waitcnt lgkmcnt(9)
	v_fma_f32 v15, -v244, v12, v15
	v_fma_f32 v15, -v245, v13, v15
	v_fma_f32 v15, -v246, v14, v15
	v_fma_f32 v15, -v51, v247, v15
	ds_read_b128 v[228:231], v5 offset:23056
	v_mov_b32_e32 v146, v60
	v_mov_b32_e32 v147, v0
	v_mov_b32_e32 v148, v1
	v_mov_b32_e32 v149, v2
	v_mov_b32_e32 v150, v3
	v_mov_b32_e32 v151, v4
	s_waitcnt lgkmcnt(9)
	v_pk_fma_f32 v[210:211], v[146:147], v[178:179], 0
	v_pk_fma_f32 v[210:211], v[148:149], v[180:181], v[210:211]
	ds_read_b128 v[232:235], v5 offset:23072
	s_waitcnt lgkmcnt(9)
	v_pk_fma_f32 v[210:211], v[150:151], v[182:183], v[210:211]
	v_pk_fma_f32 v[210:211], v[6:7], v[184:185], v[210:211]
	ds_read_b128 v[244:247], v5 offset:23088
	s_waitcnt lgkmcnt(9)
	v_pk_fma_f32 v[210:211], v[8:9], v[186:187], v[210:211]
	v_pk_fma_f32 v[210:211], v[10:11], v[188:189], v[210:211]
	ds_read_b128 v[178:181], v5 offset:23312
	s_waitcnt lgkmcnt(9)
	v_pk_fma_f32 v[210:211], v[12:13], v[190:191], v[210:211]
	v_pk_fma_f32 v[210:211], v[14:15], v[192:193], v[210:211]
	ds_read_b128 v[182:185], v5 offset:23296
	v_add_f32_e32 v16, v210, v211
	s_waitcnt lgkmcnt(8)
	v_pk_fma_f32 v[218:219], v[146:147], v[198:199], 0
	v_pk_fma_f32 v[218:219], v[148:149], v[200:201], v[218:219]
	ds_read_b128 v[186:189], v5 offset:23344
	v_pk_fma_f32 v[218:219], v[150:151], v[194:195], v[218:219]
	v_pk_fma_f32 v[218:219], v[6:7], v[196:197], v[218:219]
	ds_read_b128 v[190:193], v5 offset:23328
	s_waitcnt lgkmcnt(8)
	v_pk_fma_f32 v[218:219], v[8:9], v[206:207], v[218:219]
	v_pk_fma_f32 v[218:219], v[10:11], v[208:209], v[218:219]
	ds_read_b128 v[198:201], v5 offset:23552
	v_pk_fma_f32 v[218:219], v[12:13], v[202:203], v[218:219]
	v_pk_fma_f32 v[218:219], v[14:15], v[204:205], v[218:219]
	ds_read_b128 v[194:197], v5 offset:23568
	v_add_f32_e32 v17, v218, v219
	v_sub_f32_e32 v16, v48, v16
	v_sub_f32_e32 v17, v49, v17
	s_waitcnt lgkmcnt(9)
	v_pk_fma_f32 v[236:237], v[146:147], v[214:215], 0
	v_pk_fma_f32 v[236:237], v[148:149], v[216:217], v[236:237]
	ds_read_b128 v[206:209], v5 offset:23584
	s_waitcnt lgkmcnt(9)
	v_pk_fma_f32 v[236:237], v[150:151], v[228:229], v[236:237]
	v_pk_fma_f32 v[236:237], v[6:7], v[230:231], v[236:237]
	ds_read_b128 v[202:205], v5 offset:23600
	s_waitcnt lgkmcnt(9)
	v_pk_fma_f32 v[236:237], v[8:9], v[232:233], v[236:237]
	v_pk_fma_f32 v[236:237], v[10:11], v[234:235], v[236:237]
	ds_read_b128 v[214:217], v5 offset:23824
	s_waitcnt lgkmcnt(9)
	v_pk_fma_f32 v[236:237], v[12:13], v[244:245], v[236:237]
	v_pk_fma_f32 v[236:237], v[14:15], v[246:247], v[236:237]
	ds_read_b128 v[228:231], v5 offset:23808
	v_add_f32_e32 v18, v236, v237
	s_waitcnt lgkmcnt(8)
	v_pk_fma_f32 v[248:249], v[146:147], v[182:183], 0
	v_pk_fma_f32 v[248:249], v[148:149], v[184:185], v[248:249]
	ds_read_b128 v[232:235], v5 offset:23856
	v_pk_fma_f32 v[248:249], v[150:151], v[178:179], v[248:249]
	v_pk_fma_f32 v[248:249], v[6:7], v[180:181], v[248:249]
	ds_read_b128 v[244:247], v5 offset:23840
	s_waitcnt lgkmcnt(8)
	v_pk_fma_f32 v[248:249], v[8:9], v[190:191], v[248:249]
	v_pk_fma_f32 v[248:249], v[10:11], v[192:193], v[248:249]
	ds_read_b128 v[182:185], v5 offset:24064
	v_pk_fma_f32 v[248:249], v[12:13], v[186:187], v[248:249]
	v_pk_fma_f32 v[248:249], v[14:15], v[188:189], v[248:249]
	ds_read_b128 v[178:181], v5 offset:24080
	v_add_f32_e32 v19, v248, v249
	v_sub_f32_e32 v18, v44, v18
	v_sub_f32_e32 v19, v45, v19
	s_waitcnt lgkmcnt(9)
	v_pk_fma_f32 v[210:211], v[146:147], v[198:199], 0
	v_pk_fma_f32 v[210:211], v[148:149], v[200:201], v[210:211]
	ds_read_b128 v[190:193], v5 offset:24096
	s_waitcnt lgkmcnt(9)
	v_pk_fma_f32 v[210:211], v[150:151], v[194:195], v[210:211]
	v_pk_fma_f32 v[210:211], v[6:7], v[196:197], v[210:211]
	ds_read_b128 v[186:189], v5 offset:24112
	s_waitcnt lgkmcnt(9)
	v_pk_fma_f32 v[210:211], v[8:9], v[206:207], v[210:211]
	v_pk_fma_f32 v[210:211], v[10:11], v[208:209], v[210:211]
	ds_read_b128 v[198:201], v5 offset:24336
	s_waitcnt lgkmcnt(9)
	v_pk_fma_f32 v[210:211], v[12:13], v[202:203], v[210:211]
	v_pk_fma_f32 v[210:211], v[14:15], v[204:205], v[210:211]
	ds_read_b128 v[194:197], v5 offset:24320
	v_add_f32_e32 v20, v210, v211
	s_waitcnt lgkmcnt(8)
	v_pk_fma_f32 v[218:219], v[146:147], v[228:229], 0
	v_pk_fma_f32 v[218:219], v[148:149], v[230:231], v[218:219]
	ds_read_b128 v[206:209], v5 offset:24368
	v_pk_fma_f32 v[218:219], v[150:151], v[214:215], v[218:219]
	v_pk_fma_f32 v[218:219], v[6:7], v[216:217], v[218:219]
	ds_read_b128 v[202:205], v5 offset:24352
	s_waitcnt lgkmcnt(8)
	v_pk_fma_f32 v[218:219], v[8:9], v[244:245], v[218:219]
	v_pk_fma_f32 v[218:219], v[10:11], v[246:247], v[218:219]
	ds_read_b128 v[228:231], v5 offset:24576
	v_pk_fma_f32 v[218:219], v[12:13], v[232:233], v[218:219]
	v_pk_fma_f32 v[218:219], v[14:15], v[234:235], v[218:219]
	ds_read_b128 v[214:217], v5 offset:24592
	v_add_f32_e32 v21, v218, v219
	v_sub_f32_e32 v20, v46, v20
	v_sub_f32_e32 v21, v47, v21
	s_waitcnt lgkmcnt(9)
	v_pk_fma_f32 v[236:237], v[146:147], v[182:183], 0
	v_pk_fma_f32 v[236:237], v[148:149], v[184:185], v[236:237]
	ds_read_b128 v[244:247], v5 offset:24608
	s_waitcnt lgkmcnt(9)
	v_pk_fma_f32 v[236:237], v[150:151], v[178:179], v[236:237]
	v_pk_fma_f32 v[236:237], v[6:7], v[180:181], v[236:237]
	ds_read_b128 v[232:235], v5 offset:24624
	s_waitcnt lgkmcnt(9)
	v_pk_fma_f32 v[236:237], v[8:9], v[190:191], v[236:237]
	v_pk_fma_f32 v[236:237], v[10:11], v[192:193], v[236:237]
	ds_read_b128 v[182:185], v5 offset:24848
	s_waitcnt lgkmcnt(9)
	v_pk_fma_f32 v[236:237], v[12:13], v[186:187], v[236:237]
	v_pk_fma_f32 v[236:237], v[14:15], v[188:189], v[236:237]
	ds_read_b128 v[178:181], v5 offset:24832
	v_add_f32_e32 v22, v236, v237
	s_waitcnt lgkmcnt(8)
	v_pk_fma_f32 v[248:249], v[146:147], v[194:195], 0
	v_pk_fma_f32 v[248:249], v[148:149], v[196:197], v[248:249]
	ds_read_b128 v[190:193], v5 offset:24880
	v_pk_fma_f32 v[248:249], v[150:151], v[198:199], v[248:249]
	v_pk_fma_f32 v[248:249], v[6:7], v[200:201], v[248:249]
	ds_read_b128 v[186:189], v5 offset:24864
	s_waitcnt lgkmcnt(8)
	v_pk_fma_f32 v[248:249], v[8:9], v[202:203], v[248:249]
	v_pk_fma_f32 v[248:249], v[10:11], v[204:205], v[248:249]
	ds_read_b128 v[194:197], v5 offset:25088
	v_pk_fma_f32 v[248:249], v[12:13], v[206:207], v[248:249]
	v_pk_fma_f32 v[248:249], v[14:15], v[208:209], v[248:249]
	ds_read_b128 v[198:201], v5 offset:25104
	v_add_f32_e32 v23, v248, v249
	v_sub_f32_e32 v22, v42, v22
	v_sub_f32_e32 v23, v43, v23
	s_waitcnt lgkmcnt(9)
	v_pk_fma_f32 v[210:211], v[146:147], v[228:229], 0
	v_pk_fma_f32 v[210:211], v[148:149], v[230:231], v[210:211]
	ds_read_b128 v[202:205], v5 offset:25120
	s_waitcnt lgkmcnt(9)
	v_pk_fma_f32 v[210:211], v[150:151], v[214:215], v[210:211]
	v_pk_fma_f32 v[210:211], v[6:7], v[216:217], v[210:211]
	ds_read_b128 v[206:209], v5 offset:25136
	s_waitcnt lgkmcnt(9)
	v_pk_fma_f32 v[210:211], v[8:9], v[244:245], v[210:211]
	v_pk_fma_f32 v[210:211], v[10:11], v[246:247], v[210:211]
	ds_read_b128 v[228:231], v5 offset:25360
	s_waitcnt lgkmcnt(9)
	v_pk_fma_f32 v[210:211], v[12:13], v[232:233], v[210:211]
	v_pk_fma_f32 v[210:211], v[14:15], v[234:235], v[210:211]
	ds_read_b128 v[214:217], v5 offset:25344
	v_add_f32_e32 v24, v210, v211
	v_sub_f32_e32 v24, v40, v24
	s_waitcnt lgkmcnt(8)
	v_pk_fma_f32 v[218:219], v[146:147], v[178:179], 0
	v_pk_fma_f32 v[218:219], v[148:149], v[180:181], v[218:219]
	ds_read_b128 v[244:247], v5 offset:25392
	v_pk_fma_f32 v[218:219], v[150:151], v[182:183], v[218:219]
	v_pk_fma_f32 v[218:219], v[6:7], v[184:185], v[218:219]
	ds_read_b128 v[232:235], v5 offset:25376
	s_waitcnt lgkmcnt(8)
	v_pk_fma_f32 v[218:219], v[8:9], v[186:187], v[218:219]
	v_pk_fma_f32 v[218:219], v[10:11], v[188:189], v[218:219]
	ds_read_b128 v[178:181], v5 offset:25600
	v_pk_fma_f32 v[218:219], v[12:13], v[190:191], v[218:219]
	v_pk_fma_f32 v[218:219], v[14:15], v[192:193], v[218:219]
	ds_read_b128 v[182:185], v5 offset:25616
	v_add_f32_e32 v25, v218, v219
	v_sub_f32_e32 v25, v41, v25
	s_waitcnt lgkmcnt(9)
	v_pk_fma_f32 v[236:237], v[146:147], v[194:195], 0
	v_pk_fma_f32 v[236:237], v[148:149], v[196:197], v[236:237]
	ds_read_b128 v[186:189], v5 offset:25632
	s_waitcnt lgkmcnt(9)
	v_pk_fma_f32 v[236:237], v[150:151], v[198:199], v[236:237]
	v_pk_fma_f32 v[236:237], v[6:7], v[200:201], v[236:237]
	ds_read_b128 v[190:193], v5 offset:25648
	s_waitcnt lgkmcnt(9)
	v_pk_fma_f32 v[236:237], v[8:9], v[202:203], v[236:237]
	v_pk_fma_f32 v[236:237], v[10:11], v[204:205], v[236:237]
	ds_read_b128 v[194:197], v5 offset:25872
	s_waitcnt lgkmcnt(9)
	v_pk_fma_f32 v[236:237], v[12:13], v[206:207], v[236:237]
	v_pk_fma_f32 v[236:237], v[14:15], v[208:209], v[236:237]
	ds_read_b128 v[198:201], v5 offset:25856
	v_add_f32_e32 v26, v236, v237
	s_waitcnt lgkmcnt(8)
	v_pk_fma_f32 v[248:249], v[146:147], v[214:215], 0
	v_pk_fma_f32 v[248:249], v[148:149], v[216:217], v[248:249]
	ds_read_b128 v[202:205], v5 offset:25904
	v_pk_fma_f32 v[248:249], v[150:151], v[228:229], v[248:249]
	v_pk_fma_f32 v[248:249], v[6:7], v[230:231], v[248:249]
	ds_read_b128 v[206:209], v5 offset:25888
	s_waitcnt lgkmcnt(8)
	v_pk_fma_f32 v[248:249], v[8:9], v[232:233], v[248:249]
	v_pk_fma_f32 v[248:249], v[10:11], v[234:235], v[248:249]
	ds_read_b128 v[214:217], v5 offset:26112
	v_pk_fma_f32 v[248:249], v[12:13], v[244:245], v[248:249]
	v_pk_fma_f32 v[248:249], v[14:15], v[246:247], v[248:249]
	ds_read_b128 v[228:231], v5 offset:26128
	v_add_f32_e32 v27, v248, v249
	v_sub_f32_e32 v26, v36, v26
	v_sub_f32_e32 v27, v37, v27
	s_waitcnt lgkmcnt(9)
	v_pk_fma_f32 v[210:211], v[146:147], v[178:179], 0
	v_pk_fma_f32 v[210:211], v[148:149], v[180:181], v[210:211]
	ds_read_b128 v[232:235], v5 offset:26144
	s_waitcnt lgkmcnt(9)
	v_pk_fma_f32 v[210:211], v[150:151], v[182:183], v[210:211]
	v_pk_fma_f32 v[210:211], v[6:7], v[184:185], v[210:211]
	ds_read_b128 v[244:247], v5 offset:26160
	s_waitcnt lgkmcnt(9)
	v_pk_fma_f32 v[210:211], v[8:9], v[186:187], v[210:211]
	v_pk_fma_f32 v[210:211], v[10:11], v[188:189], v[210:211]
	ds_read_b128 v[178:181], v5 offset:26384
	s_waitcnt lgkmcnt(9)
	v_pk_fma_f32 v[210:211], v[12:13], v[190:191], v[210:211]
	v_pk_fma_f32 v[210:211], v[14:15], v[192:193], v[210:211]
	ds_read_b128 v[182:185], v5 offset:26368
	v_add_f32_e32 v28, v210, v211
	s_waitcnt lgkmcnt(8)
	v_pk_fma_f32 v[218:219], v[146:147], v[198:199], 0
	v_pk_fma_f32 v[218:219], v[148:149], v[200:201], v[218:219]
	ds_read_b128 v[186:189], v5 offset:26416
	v_pk_fma_f32 v[218:219], v[150:151], v[194:195], v[218:219]
	v_pk_fma_f32 v[218:219], v[6:7], v[196:197], v[218:219]
	ds_read_b128 v[190:193], v5 offset:26400
	s_waitcnt lgkmcnt(8)
	v_pk_fma_f32 v[218:219], v[8:9], v[206:207], v[218:219]
	v_pk_fma_f32 v[218:219], v[10:11], v[208:209], v[218:219]
	ds_read_b128 v[198:201], v5 offset:26624
	v_pk_fma_f32 v[218:219], v[12:13], v[202:203], v[218:219]
	v_pk_fma_f32 v[218:219], v[14:15], v[204:205], v[218:219]
	ds_read_b128 v[194:197], v5 offset:26640
	v_add_f32_e32 v29, v218, v219
	v_sub_f32_e32 v28, v38, v28
	v_sub_f32_e32 v29, v39, v29
	s_waitcnt lgkmcnt(9)
	v_pk_fma_f32 v[236:237], v[146:147], v[214:215], 0
	v_pk_fma_f32 v[236:237], v[148:149], v[216:217], v[236:237]
	ds_read_b128 v[206:209], v5 offset:26656
	s_waitcnt lgkmcnt(9)
	v_pk_fma_f32 v[236:237], v[150:151], v[228:229], v[236:237]
	v_pk_fma_f32 v[236:237], v[6:7], v[230:231], v[236:237]
	ds_read_b128 v[202:205], v5 offset:26672
	s_waitcnt lgkmcnt(9)
	v_pk_fma_f32 v[236:237], v[8:9], v[232:233], v[236:237]
	v_pk_fma_f32 v[236:237], v[10:11], v[234:235], v[236:237]
	ds_read_b128 v[214:217], v5 offset:26896
	s_waitcnt lgkmcnt(9)
	v_pk_fma_f32 v[236:237], v[12:13], v[244:245], v[236:237]
	v_pk_fma_f32 v[236:237], v[14:15], v[246:247], v[236:237]
	ds_read_b128 v[228:231], v5 offset:26880
	v_add_f32_e32 v44, v236, v237
	v_sub_f32_e32 v72, v32, v44
	s_waitcnt lgkmcnt(8)
	v_pk_fma_f32 v[248:249], v[146:147], v[182:183], 0
	v_pk_fma_f32 v[248:249], v[148:149], v[184:185], v[248:249]
	ds_read_b128 v[232:235], v5 offset:26928
	v_pk_fma_f32 v[248:249], v[150:151], v[178:179], v[248:249]
	v_pk_fma_f32 v[248:249], v[6:7], v[180:181], v[248:249]
	ds_read_b128 v[244:247], v5 offset:26912
	s_waitcnt lgkmcnt(8)
	v_pk_fma_f32 v[248:249], v[8:9], v[190:191], v[248:249]
	v_pk_fma_f32 v[248:249], v[10:11], v[192:193], v[248:249]
	ds_read_b128 v[182:185], v5 offset:27136
	v_pk_fma_f32 v[248:249], v[12:13], v[186:187], v[248:249]
	v_pk_fma_f32 v[248:249], v[14:15], v[188:189], v[248:249]
	ds_read_b128 v[178:181], v5 offset:27152
	v_add_f32_e32 v32, v248, v249
	v_sub_f32_e32 v32, v33, v32
	s_waitcnt lgkmcnt(9)
	v_pk_fma_f32 v[210:211], v[146:147], v[198:199], 0
	v_pk_fma_f32 v[210:211], v[148:149], v[200:201], v[210:211]
	ds_read_b128 v[190:193], v5 offset:27168
	s_waitcnt lgkmcnt(9)
	v_pk_fma_f32 v[210:211], v[150:151], v[194:195], v[210:211]
	v_pk_fma_f32 v[210:211], v[6:7], v[196:197], v[210:211]
	ds_read_b128 v[186:189], v5 offset:27184
	s_waitcnt lgkmcnt(9)
	v_pk_fma_f32 v[210:211], v[8:9], v[206:207], v[210:211]
	v_pk_fma_f32 v[210:211], v[10:11], v[208:209], v[210:211]
	ds_read_b128 v[198:201], v5 offset:27408
	s_waitcnt lgkmcnt(9)
	v_pk_fma_f32 v[210:211], v[12:13], v[202:203], v[210:211]
	v_pk_fma_f32 v[210:211], v[14:15], v[204:205], v[210:211]
	ds_read_b128 v[194:197], v5 offset:27392
	v_add_f32_e32 v33, v210, v211
	v_sub_f32_e32 v33, v34, v33
	s_waitcnt lgkmcnt(8)
	v_pk_fma_f32 v[218:219], v[146:147], v[228:229], 0
	v_pk_fma_f32 v[218:219], v[148:149], v[230:231], v[218:219]
	ds_read_b128 v[206:209], v5 offset:27440
	v_pk_fma_f32 v[218:219], v[150:151], v[214:215], v[218:219]
	v_pk_fma_f32 v[218:219], v[6:7], v[216:217], v[218:219]
	ds_read_b128 v[202:205], v5 offset:27424
	s_waitcnt lgkmcnt(8)
	v_pk_fma_f32 v[218:219], v[8:9], v[244:245], v[218:219]
	v_pk_fma_f32 v[218:219], v[10:11], v[246:247], v[218:219]
	ds_read_b128 v[228:231], v5 offset:27648
	v_pk_fma_f32 v[218:219], v[12:13], v[232:233], v[218:219]
	v_pk_fma_f32 v[218:219], v[14:15], v[234:235], v[218:219]
	ds_read_b128 v[214:217], v5 offset:27664
	v_add_f32_e32 v34, v218, v219
	v_sub_f32_e32 v34, v35, v34
	s_waitcnt lgkmcnt(9)
	v_pk_fma_f32 v[236:237], v[146:147], v[182:183], 0
	v_pk_fma_f32 v[236:237], v[148:149], v[184:185], v[236:237]
	ds_read_b128 v[244:247], v5 offset:27680
	s_waitcnt lgkmcnt(9)
	v_pk_fma_f32 v[236:237], v[150:151], v[178:179], v[236:237]
	v_pk_fma_f32 v[236:237], v[6:7], v[180:181], v[236:237]
	ds_read_b128 v[232:235], v5 offset:27696
	s_waitcnt lgkmcnt(9)
	v_pk_fma_f32 v[236:237], v[8:9], v[190:191], v[236:237]
	v_pk_fma_f32 v[236:237], v[10:11], v[192:193], v[236:237]
	ds_read_b128 v[182:185], v5 offset:27920
	s_waitcnt lgkmcnt(9)
	v_pk_fma_f32 v[236:237], v[12:13], v[186:187], v[236:237]
	v_pk_fma_f32 v[236:237], v[14:15], v[188:189], v[236:237]
	ds_read_b128 v[178:181], v5 offset:27904
	v_add_f32_e32 v35, v236, v237
	v_sub_f32_e32 v35, v30, v35
	s_waitcnt lgkmcnt(8)
	v_pk_fma_f32 v[248:249], v[146:147], v[194:195], 0
	v_pk_fma_f32 v[248:249], v[148:149], v[196:197], v[248:249]
	ds_read_b128 v[190:193], v5 offset:27952
	v_pk_fma_f32 v[248:249], v[150:151], v[198:199], v[248:249]
	v_pk_fma_f32 v[248:249], v[6:7], v[200:201], v[248:249]
	ds_read_b128 v[186:189], v5 offset:27936
	s_waitcnt lgkmcnt(8)
	v_pk_fma_f32 v[248:249], v[8:9], v[202:203], v[248:249]
	v_pk_fma_f32 v[248:249], v[10:11], v[204:205], v[248:249]
	ds_read_b128 v[194:197], v5 offset:28160
	v_pk_fma_f32 v[248:249], v[12:13], v[206:207], v[248:249]
	v_pk_fma_f32 v[248:249], v[14:15], v[208:209], v[248:249]
	ds_read_b128 v[198:201], v5 offset:28176
	v_add_f32_e32 v30, v248, v249
	v_sub_f32_e32 v36, v31, v30
	s_waitcnt lgkmcnt(9)
	v_pk_fma_f32 v[210:211], v[146:147], v[228:229], 0
	v_pk_fma_f32 v[210:211], v[148:149], v[230:231], v[210:211]
	ds_read_b128 v[202:205], v5 offset:28192
	s_waitcnt lgkmcnt(9)
	v_pk_fma_f32 v[210:211], v[150:151], v[214:215], v[210:211]
	v_pk_fma_f32 v[210:211], v[6:7], v[216:217], v[210:211]
	ds_read_b128 v[206:209], v5 offset:28208
	s_waitcnt lgkmcnt(9)
	v_pk_fma_f32 v[210:211], v[8:9], v[244:245], v[210:211]
	v_pk_fma_f32 v[210:211], v[10:11], v[246:247], v[210:211]
	ds_read_b128 v[228:231], v5 offset:28432
	s_waitcnt lgkmcnt(9)
	v_pk_fma_f32 v[210:211], v[12:13], v[232:233], v[210:211]
	v_pk_fma_f32 v[210:211], v[14:15], v[234:235], v[210:211]
	ds_read_b128 v[214:217], v5 offset:28416
	v_add_f32_e32 v30, v210, v211
	v_sub_f32_e32 v37, v62, v30
	s_waitcnt lgkmcnt(8)
	v_pk_fma_f32 v[218:219], v[146:147], v[178:179], 0
	v_pk_fma_f32 v[218:219], v[148:149], v[180:181], v[218:219]
	ds_read_b128 v[244:247], v5 offset:28464
	v_pk_fma_f32 v[218:219], v[150:151], v[182:183], v[218:219]
	v_pk_fma_f32 v[218:219], v[6:7], v[184:185], v[218:219]
	ds_read_b128 v[232:235], v5 offset:28448
	s_waitcnt lgkmcnt(8)
	v_pk_fma_f32 v[218:219], v[8:9], v[186:187], v[218:219]
	v_pk_fma_f32 v[218:219], v[10:11], v[188:189], v[218:219]
	ds_read_b128 v[178:181], v5 offset:28672
	v_pk_fma_f32 v[218:219], v[12:13], v[190:191], v[218:219]
	v_pk_fma_f32 v[218:219], v[14:15], v[192:193], v[218:219]
	ds_read_b128 v[182:185], v5 offset:28688
	v_add_f32_e32 v30, v218, v219
	v_sub_f32_e32 v38, v63, v30
	s_waitcnt lgkmcnt(9)
	v_pk_fma_f32 v[236:237], v[146:147], v[194:195], 0
	v_pk_fma_f32 v[236:237], v[148:149], v[196:197], v[236:237]
	ds_read_b128 v[186:189], v5 offset:28704
	s_waitcnt lgkmcnt(9)
	v_pk_fma_f32 v[236:237], v[150:151], v[198:199], v[236:237]
	v_pk_fma_f32 v[236:237], v[6:7], v[200:201], v[236:237]
	ds_read_b128 v[190:193], v5 offset:28720
	s_waitcnt lgkmcnt(9)
	v_pk_fma_f32 v[236:237], v[8:9], v[202:203], v[236:237]
	v_pk_fma_f32 v[236:237], v[10:11], v[204:205], v[236:237]
	ds_read_b128 v[194:197], v5 offset:28944
	s_waitcnt lgkmcnt(9)
	v_pk_fma_f32 v[236:237], v[12:13], v[206:207], v[236:237]
	v_pk_fma_f32 v[236:237], v[14:15], v[208:209], v[236:237]
	ds_read_b128 v[198:201], v5 offset:28928
	v_add_f32_e32 v30, v236, v237
	v_sub_f32_e32 v39, v70, v30
	s_waitcnt lgkmcnt(8)
	v_pk_fma_f32 v[248:249], v[146:147], v[214:215], 0
	v_pk_fma_f32 v[248:249], v[148:149], v[216:217], v[248:249]
	ds_read_b128 v[202:205], v5 offset:28976
	v_pk_fma_f32 v[248:249], v[150:151], v[228:229], v[248:249]
	v_pk_fma_f32 v[248:249], v[6:7], v[230:231], v[248:249]
	ds_read_b128 v[206:209], v5 offset:28960
	s_waitcnt lgkmcnt(8)
	v_pk_fma_f32 v[248:249], v[8:9], v[232:233], v[248:249]
	v_pk_fma_f32 v[248:249], v[10:11], v[234:235], v[248:249]
	ds_read_b128 v[214:217], v5 offset:29184
	v_pk_fma_f32 v[248:249], v[12:13], v[244:245], v[248:249]
	v_pk_fma_f32 v[248:249], v[14:15], v[246:247], v[248:249]
	ds_read_b128 v[228:231], v5 offset:29200
	v_add_f32_e32 v30, v248, v249
	v_sub_f32_e32 v40, v71, v30
	s_waitcnt lgkmcnt(9)
	v_pk_fma_f32 v[210:211], v[146:147], v[178:179], 0
	v_pk_fma_f32 v[210:211], v[148:149], v[180:181], v[210:211]
	ds_read_b128 v[232:235], v5 offset:29216
	s_waitcnt lgkmcnt(9)
	v_pk_fma_f32 v[210:211], v[150:151], v[182:183], v[210:211]
	v_pk_fma_f32 v[210:211], v[6:7], v[184:185], v[210:211]
	ds_read_b128 v[244:247], v5 offset:29232
	s_waitcnt lgkmcnt(9)
	v_pk_fma_f32 v[210:211], v[8:9], v[186:187], v[210:211]
	v_pk_fma_f32 v[210:211], v[10:11], v[188:189], v[210:211]
	ds_read_b128 v[178:181], v5 offset:29456
	s_waitcnt lgkmcnt(9)
	v_pk_fma_f32 v[210:211], v[12:13], v[190:191], v[210:211]
	v_pk_fma_f32 v[210:211], v[14:15], v[192:193], v[210:211]
	ds_read_b128 v[182:185], v5 offset:29440
	v_add_f32_e32 v30, v210, v211
	v_sub_f32_e32 v41, v58, v30
	s_waitcnt lgkmcnt(8)
	v_pk_fma_f32 v[218:219], v[146:147], v[198:199], 0
	v_pk_fma_f32 v[218:219], v[148:149], v[200:201], v[218:219]
	ds_read_b128 v[186:189], v5 offset:29488
	v_pk_fma_f32 v[218:219], v[150:151], v[194:195], v[218:219]
	v_pk_fma_f32 v[218:219], v[6:7], v[196:197], v[218:219]
	ds_read_b128 v[190:193], v5 offset:29472
	s_waitcnt lgkmcnt(8)
	v_pk_fma_f32 v[218:219], v[8:9], v[206:207], v[218:219]
	v_pk_fma_f32 v[218:219], v[10:11], v[208:209], v[218:219]
	ds_read_b128 v[198:201], v5 offset:29696
	v_pk_fma_f32 v[218:219], v[12:13], v[202:203], v[218:219]
	v_pk_fma_f32 v[218:219], v[14:15], v[204:205], v[218:219]
	ds_read_b128 v[194:197], v5 offset:29712
	v_add_f32_e32 v30, v218, v219
	v_sub_f32_e32 v42, v59, v30
	s_waitcnt lgkmcnt(9)
	v_pk_fma_f32 v[236:237], v[146:147], v[214:215], 0
	v_pk_fma_f32 v[236:237], v[148:149], v[216:217], v[236:237]
	ds_read_b128 v[206:209], v5 offset:29728
	s_waitcnt lgkmcnt(9)
	v_pk_fma_f32 v[236:237], v[150:151], v[228:229], v[236:237]
	v_pk_fma_f32 v[236:237], v[6:7], v[230:231], v[236:237]
	ds_read_b128 v[202:205], v5 offset:29744
	s_waitcnt lgkmcnt(9)
	v_pk_fma_f32 v[236:237], v[8:9], v[232:233], v[236:237]
	v_pk_fma_f32 v[236:237], v[10:11], v[234:235], v[236:237]
	ds_read_b128 v[214:217], v5 offset:29968
	s_waitcnt lgkmcnt(9)
	v_pk_fma_f32 v[236:237], v[12:13], v[244:245], v[236:237]
	v_pk_fma_f32 v[236:237], v[14:15], v[246:247], v[236:237]
	ds_read_b128 v[228:231], v5 offset:29952
	v_add_f32_e32 v30, v236, v237
	v_sub_f32_e32 v43, v56, v30
	s_waitcnt lgkmcnt(8)
	v_pk_fma_f32 v[248:249], v[146:147], v[182:183], 0
	v_pk_fma_f32 v[248:249], v[148:149], v[184:185], v[248:249]
	ds_read_b128 v[232:235], v5 offset:30000
	v_pk_fma_f32 v[248:249], v[150:151], v[178:179], v[248:249]
	v_pk_fma_f32 v[248:249], v[6:7], v[180:181], v[248:249]
	ds_read_b128 v[244:247], v5 offset:29984
	s_waitcnt lgkmcnt(8)
	v_pk_fma_f32 v[248:249], v[8:9], v[190:191], v[248:249]
	v_pk_fma_f32 v[248:249], v[10:11], v[192:193], v[248:249]
	ds_read_b128 v[182:185], v5 offset:30208
	v_pk_fma_f32 v[248:249], v[12:13], v[186:187], v[248:249]
	v_pk_fma_f32 v[248:249], v[14:15], v[188:189], v[248:249]
	ds_read_b128 v[178:181], v5 offset:30224
	v_add_f32_e32 v30, v248, v249
	v_sub_f32_e32 v44, v57, v30
	s_waitcnt lgkmcnt(9)
	v_pk_fma_f32 v[210:211], v[146:147], v[198:199], 0
	v_pk_fma_f32 v[210:211], v[148:149], v[200:201], v[210:211]
	ds_read_b128 v[190:193], v5 offset:30240
	s_waitcnt lgkmcnt(9)
	v_pk_fma_f32 v[210:211], v[150:151], v[194:195], v[210:211]
	v_pk_fma_f32 v[210:211], v[6:7], v[196:197], v[210:211]
	ds_read_b128 v[186:189], v5 offset:30256
	s_waitcnt lgkmcnt(9)
	v_pk_fma_f32 v[210:211], v[8:9], v[206:207], v[210:211]
	v_pk_fma_f32 v[210:211], v[10:11], v[208:209], v[210:211]
	ds_read_b128 v[198:201], v5 offset:30480
	s_waitcnt lgkmcnt(9)
	v_pk_fma_f32 v[210:211], v[12:13], v[202:203], v[210:211]
	v_pk_fma_f32 v[210:211], v[14:15], v[204:205], v[210:211]
	ds_read_b128 v[194:197], v5 offset:30464
	v_add_f32_e32 v30, v210, v211
	v_sub_f32_e32 v45, v84, v30
	s_waitcnt lgkmcnt(8)
	v_pk_fma_f32 v[218:219], v[146:147], v[228:229], 0
	v_pk_fma_f32 v[218:219], v[148:149], v[230:231], v[218:219]
	ds_read_b128 v[206:209], v5 offset:30512
	v_pk_fma_f32 v[218:219], v[150:151], v[214:215], v[218:219]
	v_pk_fma_f32 v[218:219], v[6:7], v[216:217], v[218:219]
	ds_read_b128 v[202:205], v5 offset:30496
	s_waitcnt lgkmcnt(8)
	v_pk_fma_f32 v[218:219], v[8:9], v[244:245], v[218:219]
	v_pk_fma_f32 v[218:219], v[10:11], v[246:247], v[218:219]
	ds_read_b128 v[228:231], v5 offset:30720
	v_pk_fma_f32 v[218:219], v[12:13], v[232:233], v[218:219]
	v_pk_fma_f32 v[218:219], v[14:15], v[234:235], v[218:219]
	ds_read_b128 v[214:217], v5 offset:30736
	v_add_f32_e32 v30, v218, v219
	v_sub_f32_e32 v46, v85, v30
	s_waitcnt lgkmcnt(9)
	v_pk_fma_f32 v[236:237], v[146:147], v[182:183], 0
	v_pk_fma_f32 v[236:237], v[148:149], v[184:185], v[236:237]
	ds_read_b128 v[244:247], v5 offset:30752
	s_waitcnt lgkmcnt(9)
	v_pk_fma_f32 v[236:237], v[150:151], v[178:179], v[236:237]
	v_pk_fma_f32 v[236:237], v[6:7], v[180:181], v[236:237]
	ds_read_b128 v[232:235], v5 offset:30768
	s_waitcnt lgkmcnt(9)
	v_pk_fma_f32 v[236:237], v[8:9], v[190:191], v[236:237]
	v_pk_fma_f32 v[236:237], v[10:11], v[192:193], v[236:237]
	ds_read_b128 v[182:185], v5 offset:30992
	s_waitcnt lgkmcnt(9)
	v_pk_fma_f32 v[236:237], v[12:13], v[186:187], v[236:237]
	v_pk_fma_f32 v[236:237], v[14:15], v[188:189], v[236:237]
	ds_read_b128 v[178:181], v5 offset:30976
	v_add_f32_e32 v30, v236, v237
	v_sub_f32_e32 v47, v78, v30
	s_waitcnt lgkmcnt(8)
	v_pk_fma_f32 v[248:249], v[146:147], v[194:195], 0
	v_pk_fma_f32 v[248:249], v[148:149], v[196:197], v[248:249]
	ds_read_b128 v[190:193], v5 offset:31024
	v_pk_fma_f32 v[248:249], v[150:151], v[198:199], v[248:249]
	v_pk_fma_f32 v[248:249], v[6:7], v[200:201], v[248:249]
	ds_read_b128 v[186:189], v5 offset:31008
	s_waitcnt lgkmcnt(8)
	v_pk_fma_f32 v[248:249], v[8:9], v[202:203], v[248:249]
	v_pk_fma_f32 v[248:249], v[10:11], v[204:205], v[248:249]
	ds_read_b128 v[194:197], v5 offset:31232
	v_pk_fma_f32 v[248:249], v[12:13], v[206:207], v[248:249]
	v_pk_fma_f32 v[248:249], v[14:15], v[208:209], v[248:249]
	ds_read_b128 v[198:201], v5 offset:31248
	v_add_f32_e32 v30, v248, v249
	v_sub_f32_e32 v48, v79, v30
	s_waitcnt lgkmcnt(9)
	v_pk_fma_f32 v[210:211], v[146:147], v[228:229], 0
	v_pk_fma_f32 v[210:211], v[148:149], v[230:231], v[210:211]
	ds_read_b128 v[202:205], v5 offset:31264
	s_waitcnt lgkmcnt(9)
	v_pk_fma_f32 v[210:211], v[150:151], v[214:215], v[210:211]
	v_pk_fma_f32 v[210:211], v[6:7], v[216:217], v[210:211]
	ds_read_b128 v[206:209], v5 offset:31280
	s_waitcnt lgkmcnt(9)
	v_pk_fma_f32 v[210:211], v[8:9], v[244:245], v[210:211]
	v_pk_fma_f32 v[210:211], v[10:11], v[246:247], v[210:211]
	ds_read_b128 v[228:231], v5 offset:31504
	s_waitcnt lgkmcnt(9)
	v_pk_fma_f32 v[210:211], v[12:13], v[232:233], v[210:211]
	v_pk_fma_f32 v[210:211], v[14:15], v[234:235], v[210:211]
	ds_read_b128 v[214:217], v5 offset:31488
	v_add_f32_e32 v30, v210, v211
	v_sub_f32_e32 v49, v76, v30
	s_waitcnt lgkmcnt(8)
	v_pk_fma_f32 v[218:219], v[146:147], v[178:179], 0
	v_pk_fma_f32 v[218:219], v[148:149], v[180:181], v[218:219]
	ds_read_b128 v[244:247], v5 offset:31536
	v_pk_fma_f32 v[218:219], v[150:151], v[182:183], v[218:219]
	v_pk_fma_f32 v[218:219], v[6:7], v[184:185], v[218:219]
	ds_read_b128 v[232:235], v5 offset:31520
	s_waitcnt lgkmcnt(8)
	v_pk_fma_f32 v[218:219], v[8:9], v[186:187], v[218:219]
	v_pk_fma_f32 v[218:219], v[10:11], v[188:189], v[218:219]
	ds_read_b128 v[178:181], v5 offset:31744
	v_pk_fma_f32 v[218:219], v[12:13], v[190:191], v[218:219]
	v_pk_fma_f32 v[218:219], v[14:15], v[192:193], v[218:219]
	ds_read_b128 v[182:185], v5 offset:31760
	v_add_f32_e32 v30, v218, v219
	v_sub_f32_e32 v50, v77, v30
	s_waitcnt lgkmcnt(9)
	v_pk_fma_f32 v[236:237], v[146:147], v[194:195], 0
	v_pk_fma_f32 v[236:237], v[148:149], v[196:197], v[236:237]
	ds_read_b128 v[186:189], v5 offset:31776
	s_waitcnt lgkmcnt(9)
	v_pk_fma_f32 v[236:237], v[150:151], v[198:199], v[236:237]
	v_pk_fma_f32 v[236:237], v[6:7], v[200:201], v[236:237]
	ds_read_b128 v[190:193], v5 offset:31792
	s_waitcnt lgkmcnt(9)
	v_pk_fma_f32 v[236:237], v[8:9], v[202:203], v[236:237]
	v_pk_fma_f32 v[236:237], v[10:11], v[204:205], v[236:237]
	ds_read_b128 v[194:197], v5 offset:32016
	s_waitcnt lgkmcnt(9)
	v_pk_fma_f32 v[236:237], v[12:13], v[206:207], v[236:237]
	v_pk_fma_f32 v[236:237], v[14:15], v[208:209], v[236:237]
	ds_read_b128 v[198:201], v5 offset:32000
	v_add_f32_e32 v30, v236, v237
	v_sub_f32_e32 v51, v74, v30
	s_waitcnt lgkmcnt(8)
	v_pk_fma_f32 v[248:249], v[146:147], v[214:215], 0
	v_pk_fma_f32 v[248:249], v[148:149], v[216:217], v[248:249]
	ds_read_b128 v[202:205], v5 offset:32048
	v_pk_fma_f32 v[248:249], v[150:151], v[228:229], v[248:249]
	v_pk_fma_f32 v[248:249], v[6:7], v[230:231], v[248:249]
	ds_read_b128 v[206:209], v5 offset:32032
	s_waitcnt lgkmcnt(8)
	v_pk_fma_f32 v[248:249], v[8:9], v[232:233], v[248:249]
	v_pk_fma_f32 v[248:249], v[10:11], v[234:235], v[248:249]
	ds_read_b128 v[214:217], v5 offset:32256
	v_pk_fma_f32 v[248:249], v[12:13], v[244:245], v[248:249]
	v_pk_fma_f32 v[248:249], v[14:15], v[246:247], v[248:249]
	ds_read_b128 v[228:231], v5 offset:32272
	v_add_f32_e32 v30, v248, v249
	v_sub_f32_e32 v52, v75, v30
	s_waitcnt lgkmcnt(9)
	v_pk_fma_f32 v[210:211], v[146:147], v[178:179], 0
	v_pk_fma_f32 v[210:211], v[148:149], v[180:181], v[210:211]
	ds_read_b128 v[232:235], v5 offset:32288
	s_waitcnt lgkmcnt(9)
	v_pk_fma_f32 v[210:211], v[150:151], v[182:183], v[210:211]
	v_pk_fma_f32 v[210:211], v[6:7], v[184:185], v[210:211]
	ds_read_b128 v[244:247], v5 offset:32304
	s_waitcnt lgkmcnt(9)
	v_pk_fma_f32 v[210:211], v[8:9], v[186:187], v[210:211]
	v_pk_fma_f32 v[210:211], v[10:11], v[188:189], v[210:211]
	ds_read_b128 v[178:181], v5 offset:32528
	s_waitcnt lgkmcnt(9)
	v_pk_fma_f32 v[210:211], v[12:13], v[190:191], v[210:211]
	v_pk_fma_f32 v[210:211], v[14:15], v[192:193], v[210:211]
	ds_read_b128 v[182:185], v5 offset:32512
	v_add_f32_e32 v30, v210, v211
	v_sub_f32_e32 v53, v92, v30
	s_waitcnt lgkmcnt(8)
	v_pk_fma_f32 v[218:219], v[146:147], v[198:199], 0
	v_pk_fma_f32 v[218:219], v[148:149], v[200:201], v[218:219]
	ds_read_b128 v[186:189], v5 offset:32560
	v_pk_fma_f32 v[218:219], v[150:151], v[194:195], v[218:219]
	v_pk_fma_f32 v[218:219], v[6:7], v[196:197], v[218:219]
	ds_read_b128 v[190:193], v5 offset:32544
	s_waitcnt lgkmcnt(8)
	v_pk_fma_f32 v[218:219], v[8:9], v[206:207], v[218:219]
	v_pk_fma_f32 v[218:219], v[10:11], v[208:209], v[218:219]
	ds_read_b128 v[198:201], v5 offset:32768
	v_pk_fma_f32 v[218:219], v[12:13], v[202:203], v[218:219]
	v_pk_fma_f32 v[218:219], v[14:15], v[204:205], v[218:219]
	ds_read_b128 v[194:197], v5 offset:32784
	v_add_f32_e32 v30, v218, v219
	v_sub_f32_e32 v54, v93, v30
	s_waitcnt lgkmcnt(9)
	v_pk_fma_f32 v[236:237], v[146:147], v[214:215], 0
	v_pk_fma_f32 v[236:237], v[148:149], v[216:217], v[236:237]
	ds_read_b128 v[206:209], v5 offset:32800
	s_waitcnt lgkmcnt(9)
	v_pk_fma_f32 v[236:237], v[150:151], v[228:229], v[236:237]
	v_pk_fma_f32 v[236:237], v[6:7], v[230:231], v[236:237]
	ds_read_b128 v[202:205], v5 offset:32816
	s_waitcnt lgkmcnt(9)
	v_pk_fma_f32 v[236:237], v[8:9], v[232:233], v[236:237]
	v_pk_fma_f32 v[236:237], v[10:11], v[234:235], v[236:237]
	ds_read_b128 v[214:217], v5 offset:33040
	s_waitcnt lgkmcnt(9)
	v_pk_fma_f32 v[236:237], v[12:13], v[244:245], v[236:237]
	v_pk_fma_f32 v[236:237], v[14:15], v[246:247], v[236:237]
	ds_read_b128 v[228:231], v5 offset:33024
	v_add_f32_e32 v30, v236, v237
	v_sub_f32_e32 v55, v88, v30
	s_waitcnt lgkmcnt(8)
	v_pk_fma_f32 v[248:249], v[146:147], v[182:183], 0
	v_pk_fma_f32 v[248:249], v[148:149], v[184:185], v[248:249]
	ds_read_b128 v[232:235], v5 offset:33072
	v_pk_fma_f32 v[248:249], v[150:151], v[178:179], v[248:249]
	v_pk_fma_f32 v[248:249], v[6:7], v[180:181], v[248:249]
	ds_read_b128 v[244:247], v5 offset:33056
	s_waitcnt lgkmcnt(8)
	v_pk_fma_f32 v[248:249], v[8:9], v[190:191], v[248:249]
	v_pk_fma_f32 v[248:249], v[10:11], v[192:193], v[248:249]
	ds_read_b128 v[182:185], v5 offset:33280
	v_pk_fma_f32 v[248:249], v[12:13], v[186:187], v[248:249]
	v_pk_fma_f32 v[248:249], v[14:15], v[188:189], v[248:249]
	ds_read_b128 v[178:181], v5 offset:33296
	v_add_f32_e32 v30, v248, v249
	v_sub_f32_e32 v56, v89, v30
	s_waitcnt lgkmcnt(9)
	v_pk_fma_f32 v[210:211], v[146:147], v[198:199], 0
	v_pk_fma_f32 v[210:211], v[148:149], v[200:201], v[210:211]
	ds_read_b128 v[190:193], v5 offset:33312
	s_waitcnt lgkmcnt(9)
	v_pk_fma_f32 v[210:211], v[150:151], v[194:195], v[210:211]
	v_pk_fma_f32 v[210:211], v[6:7], v[196:197], v[210:211]
	ds_read_b128 v[186:189], v5 offset:33328
	s_waitcnt lgkmcnt(9)
	v_pk_fma_f32 v[210:211], v[8:9], v[206:207], v[210:211]
	v_pk_fma_f32 v[210:211], v[10:11], v[208:209], v[210:211]
	ds_read_b128 v[198:201], v5 offset:33552
	s_waitcnt lgkmcnt(9)
	v_pk_fma_f32 v[210:211], v[12:13], v[202:203], v[210:211]
	v_pk_fma_f32 v[210:211], v[14:15], v[204:205], v[210:211]
	ds_read_b128 v[194:197], v5 offset:33536
	v_add_f32_e32 v30, v210, v211
	v_sub_f32_e32 v57, v94, v30
	s_waitcnt lgkmcnt(8)
	v_pk_fma_f32 v[218:219], v[146:147], v[228:229], 0
	v_pk_fma_f32 v[218:219], v[148:149], v[230:231], v[218:219]
	ds_read_b128 v[206:209], v5 offset:33584
	v_pk_fma_f32 v[218:219], v[150:151], v[214:215], v[218:219]
	v_pk_fma_f32 v[218:219], v[6:7], v[216:217], v[218:219]
	ds_read_b128 v[202:205], v5 offset:33568
	s_waitcnt lgkmcnt(8)
	v_pk_fma_f32 v[218:219], v[8:9], v[244:245], v[218:219]
	v_pk_fma_f32 v[218:219], v[10:11], v[246:247], v[218:219]
	ds_read_b128 v[228:231], v5 offset:33792
	v_pk_fma_f32 v[218:219], v[12:13], v[232:233], v[218:219]
	v_pk_fma_f32 v[218:219], v[14:15], v[234:235], v[218:219]
	ds_read_b128 v[214:217], v5 offset:33808
	v_add_f32_e32 v30, v218, v219
	v_sub_f32_e32 v58, v95, v30
	s_waitcnt lgkmcnt(9)
	v_pk_fma_f32 v[236:237], v[146:147], v[182:183], 0
	v_pk_fma_f32 v[236:237], v[148:149], v[184:185], v[236:237]
	ds_read_b128 v[244:247], v5 offset:33824
	s_waitcnt lgkmcnt(9)
	v_pk_fma_f32 v[236:237], v[150:151], v[178:179], v[236:237]
	v_pk_fma_f32 v[236:237], v[6:7], v[180:181], v[236:237]
	ds_read_b128 v[232:235], v5 offset:33840
	s_waitcnt lgkmcnt(9)
	v_pk_fma_f32 v[236:237], v[8:9], v[190:191], v[236:237]
	v_pk_fma_f32 v[236:237], v[10:11], v[192:193], v[236:237]
	ds_read_b128 v[182:185], v5 offset:34064
	s_waitcnt lgkmcnt(9)
	v_pk_fma_f32 v[236:237], v[12:13], v[186:187], v[236:237]
	v_pk_fma_f32 v[236:237], v[14:15], v[188:189], v[236:237]
	ds_read_b128 v[178:181], v5 offset:34048
	v_add_f32_e32 v30, v236, v237
	v_sub_f32_e32 v59, v90, v30
	s_waitcnt lgkmcnt(8)
	v_pk_fma_f32 v[248:249], v[146:147], v[194:195], 0
	v_pk_fma_f32 v[248:249], v[148:149], v[196:197], v[248:249]
	ds_read_b128 v[190:193], v5 offset:34096
	v_pk_fma_f32 v[248:249], v[150:151], v[198:199], v[248:249]
	v_pk_fma_f32 v[248:249], v[6:7], v[200:201], v[248:249]
	ds_read_b128 v[186:189], v5 offset:34080
	s_waitcnt lgkmcnt(8)
	v_pk_fma_f32 v[248:249], v[8:9], v[202:203], v[248:249]
	v_pk_fma_f32 v[248:249], v[10:11], v[204:205], v[248:249]
	ds_read_b128 v[194:197], v5 offset:34304
	v_pk_fma_f32 v[248:249], v[12:13], v[206:207], v[248:249]
	v_pk_fma_f32 v[248:249], v[14:15], v[208:209], v[248:249]
	ds_read_b128 v[198:201], v5 offset:34320
	v_add_f32_e32 v30, v248, v249
	v_sub_f32_e32 v61, v91, v30
	s_waitcnt lgkmcnt(9)
	v_pk_fma_f32 v[210:211], v[146:147], v[228:229], 0
	v_pk_fma_f32 v[210:211], v[148:149], v[230:231], v[210:211]
	ds_read_b128 v[202:205], v5 offset:34336
	s_waitcnt lgkmcnt(9)
	v_pk_fma_f32 v[210:211], v[150:151], v[214:215], v[210:211]
	v_pk_fma_f32 v[210:211], v[6:7], v[216:217], v[210:211]
	ds_read_b128 v[206:209], v5 offset:34352
	s_waitcnt lgkmcnt(9)
	v_pk_fma_f32 v[210:211], v[8:9], v[244:245], v[210:211]
	v_pk_fma_f32 v[210:211], v[10:11], v[246:247], v[210:211]
	ds_read_b128 v[228:231], v5 offset:34576
	s_waitcnt lgkmcnt(9)
	v_pk_fma_f32 v[210:211], v[12:13], v[232:233], v[210:211]
	v_pk_fma_f32 v[210:211], v[14:15], v[234:235], v[210:211]
	ds_read_b128 v[214:217], v5 offset:34560
	v_add_f32_e32 v30, v210, v211
	v_sub_f32_e32 v62, v96, v30
	s_waitcnt lgkmcnt(8)
	v_pk_fma_f32 v[218:219], v[146:147], v[178:179], 0
	v_pk_fma_f32 v[218:219], v[148:149], v[180:181], v[218:219]
	ds_read_b128 v[244:247], v5 offset:34608
	v_pk_fma_f32 v[218:219], v[150:151], v[182:183], v[218:219]
	v_pk_fma_f32 v[218:219], v[6:7], v[184:185], v[218:219]
	ds_read_b128 v[232:235], v5 offset:34592
	s_waitcnt lgkmcnt(8)
	v_pk_fma_f32 v[218:219], v[8:9], v[186:187], v[218:219]
	v_pk_fma_f32 v[218:219], v[10:11], v[188:189], v[218:219]
	ds_read_b128 v[178:181], v5 offset:22848
	v_pk_fma_f32 v[218:219], v[12:13], v[190:191], v[218:219]
	v_pk_fma_f32 v[218:219], v[14:15], v[192:193], v[218:219]
	ds_read_b128 v[182:185], v5 offset:23104
	v_add_f32_e32 v30, v218, v219
	v_sub_f32_e32 v63, v97, v30
	s_waitcnt lgkmcnt(9)
	v_pk_fma_f32 v[236:237], v[146:147], v[194:195], 0
	v_pk_fma_f32 v[236:237], v[148:149], v[196:197], v[236:237]
	ds_read_b128 v[186:189], v5 offset:23360
	s_waitcnt lgkmcnt(9)
	v_pk_fma_f32 v[236:237], v[150:151], v[198:199], v[236:237]
	v_pk_fma_f32 v[236:237], v[6:7], v[200:201], v[236:237]
	ds_read_b128 v[190:193], v5 offset:23616
	s_waitcnt lgkmcnt(9)
	v_pk_fma_f32 v[236:237], v[8:9], v[202:203], v[236:237]
	v_pk_fma_f32 v[236:237], v[10:11], v[204:205], v[236:237]
	ds_read_b128 v[194:197], v5 offset:23872
	s_waitcnt lgkmcnt(9)
	v_pk_fma_f32 v[236:237], v[12:13], v[206:207], v[236:237]
	v_pk_fma_f32 v[236:237], v[14:15], v[208:209], v[236:237]
	ds_read_b128 v[198:201], v5 offset:23888
	v_add_f32_e32 v30, v236, v237
	v_sub_f32_e32 v70, v98, v30
	s_waitcnt lgkmcnt(8)
	v_pk_fma_f32 v[248:249], v[146:147], v[214:215], 0
	v_pk_fma_f32 v[248:249], v[148:149], v[216:217], v[248:249]
	ds_read_b128 v[202:205], v5 offset:24128
	v_pk_fma_f32 v[248:249], v[150:151], v[228:229], v[248:249]
	v_pk_fma_f32 v[248:249], v[6:7], v[230:231], v[248:249]
	ds_read_b128 v[206:209], v5 offset:24144
	s_waitcnt lgkmcnt(8)
	v_pk_fma_f32 v[248:249], v[8:9], v[232:233], v[248:249]
	v_pk_fma_f32 v[248:249], v[10:11], v[234:235], v[248:249]
	ds_read_b128 v[214:217], v5 offset:24384
	v_pk_fma_f32 v[248:249], v[12:13], v[244:245], v[248:249]
	v_pk_fma_f32 v[248:249], v[14:15], v[246:247], v[248:249]
	ds_read_b128 v[228:231], v5 offset:24400
	v_add_f32_e32 v30, v248, v249
	v_sub_f32_e32 v71, v99, v30
	s_waitcnt lgkmcnt(9)
	v_fma_f32 v30, -v16, v178, v17
	v_fma_f32 v17, -v17, v179, v30
	v_fma_f32 v17, -v18, v180, v17
	v_fma_f32 v17, -v19, v181, v17
	ds_read_b128 v[232:235], v5 offset:24640
	s_waitcnt lgkmcnt(9)
	v_fma_f32 v30, -v16, v182, v18
	v_fma_f32 v30, -v183, v17, v30
	v_fma_f32 v18, -v18, v184, v30
	v_fma_f32 v18, -v19, v185, v18
	ds_read_b128 v[244:247], v5 offset:24656
	s_waitcnt lgkmcnt(9)
	v_fma_f32 v30, -v16, v186, v19
	v_fma_f32 v30, -v187, v17, v30
	v_fma_f32 v30, -v188, v18, v30
	v_fma_f32 v19, -v19, v189, v30
	ds_read_b128 v[178:181], v5 offset:24896
	s_waitcnt lgkmcnt(9)
	v_fma_f32 v20, -v16, v190, v20
	v_fma_f32 v20, -v191, v17, v20
	v_fma_f32 v20, -v192, v18, v20
	v_fma_f32 v20, -v193, v19, v20
	ds_read_b128 v[182:185], v5 offset:24912
	s_waitcnt lgkmcnt(9)
	v_fma_f32 v30, -v16, v194, v21
	v_fma_f32 v30, -v195, v17, v30
	v_fma_f32 v30, -v196, v18, v30
	v_fma_f32 v30, -v197, v19, v30
	ds_read_b128 v[186:189], v5 offset:24928
	s_waitcnt lgkmcnt(9)
	v_fma_f32 v30, -v198, v20, v30
	v_fma_f32 v21, -v21, v199, v30
	v_fma_f32 v21, -v22, v200, v21
	v_fma_f32 v21, -v23, v201, v21
	ds_read_b128 v[190:193], v5 offset:25152
	s_waitcnt lgkmcnt(9)
	v_fma_f32 v30, -v16, v202, v22
	v_fma_f32 v30, -v17, v203, v30
	v_fma_f32 v30, -v204, v18, v30
	v_fma_f32 v30, -v205, v19, v30
	ds_read_b128 v[194:197], v5 offset:25168
	s_waitcnt lgkmcnt(9)
	v_fma_f32 v30, -v206, v20, v30
	v_fma_f32 v30, -v207, v21, v30
	v_fma_f32 v22, -v22, v208, v30
	v_fma_f32 v22, -v23, v209, v22
	ds_read_b128 v[198:201], v5 offset:25184
	s_waitcnt lgkmcnt(9)
	v_fma_f32 v30, -v16, v214, v23
	v_fma_f32 v30, -v17, v215, v30
	v_fma_f32 v30, -v216, v18, v30
	v_fma_f32 v30, -v217, v19, v30
	ds_read_b128 v[202:205], v5 offset:25408
	s_waitcnt lgkmcnt(9)
	v_fma_f32 v30, -v228, v20, v30
	v_fma_f32 v30, -v229, v21, v30
	v_fma_f32 v30, -v230, v22, v30
	v_fma_f32 v23, -v23, v231, v30
	ds_read_b128 v[206:209], v5 offset:25424
	s_waitcnt lgkmcnt(9)
	v_fma_f32 v24, -v16, v232, v24
	v_fma_f32 v24, -v17, v233, v24
	v_fma_f32 v24, -v18, v234, v24
	v_fma_f32 v24, -v235, v19, v24
	ds_read_b128 v[214:217], v5 offset:25440
	s_waitcnt lgkmcnt(9)
	v_fma_f32 v24, -v244, v20, v24
	v_fma_f32 v24, -v245, v21, v24
	v_fma_f32 v24, -v246, v22, v24
	v_fma_f32 v24, -v247, v23, v24
	ds_read_b128 v[228:231], v5 offset:25664
	s_waitcnt lgkmcnt(9)
	v_fma_f32 v30, -v16, v178, v25
	v_fma_f32 v30, -v17, v179, v30
	v_fma_f32 v30, -v18, v180, v30
	v_fma_f32 v30, -v181, v19, v30
	ds_read_b128 v[232:235], v5 offset:25680
	s_waitcnt lgkmcnt(9)
	v_fma_f32 v30, -v182, v20, v30
	v_fma_f32 v30, -v183, v21, v30
	v_fma_f32 v30, -v184, v22, v30
	v_fma_f32 v30, -v185, v23, v30
	ds_read_b128 v[244:247], v5 offset:25696
	s_waitcnt lgkmcnt(9)
	v_fma_f32 v30, -v186, v24, v30
	v_fma_f32 v25, -v25, v187, v30
	v_fma_f32 v25, -v26, v188, v25
	v_fma_f32 v25, -v27, v189, v25
	ds_read_b128 v[178:181], v5 offset:25920
	s_waitcnt lgkmcnt(9)
	v_fma_f32 v30, -v16, v190, v26
	v_fma_f32 v30, -v17, v191, v30
	v_fma_f32 v30, -v18, v192, v30
	v_fma_f32 v30, -v19, v193, v30
	ds_read_b128 v[182:185], v5 offset:25936
	s_waitcnt lgkmcnt(9)
	v_fma_f32 v30, -v20, v194, v30
	v_fma_f32 v30, -v195, v21, v30
	v_fma_f32 v30, -v196, v22, v30
	v_fma_f32 v30, -v197, v23, v30
	ds_read_b128 v[186:189], v5 offset:25952
	s_waitcnt lgkmcnt(9)
	v_fma_f32 v30, -v198, v24, v30
	v_fma_f32 v30, -v199, v25, v30
	v_fma_f32 v26, -v26, v200, v30
	v_fma_f32 v26, -v27, v201, v26
	ds_read_b128 v[190:193], v5 offset:25968
	s_waitcnt lgkmcnt(9)
	v_fma_f32 v30, -v16, v202, v27
	v_fma_f32 v30, -v17, v203, v30
	v_fma_f32 v30, -v18, v204, v30
	v_fma_f32 v30, -v19, v205, v30
	ds_read_b128 v[194:197], v5 offset:26176
	s_waitcnt lgkmcnt(9)
	v_fma_f32 v30, -v20, v206, v30
	v_fma_f32 v30, -v207, v21, v30
	v_fma_f32 v30, -v208, v22, v30
	v_fma_f32 v30, -v209, v23, v30
	ds_read_b128 v[198:201], v5 offset:26192
	s_waitcnt lgkmcnt(9)
	v_fma_f32 v30, -v214, v24, v30
	v_fma_f32 v30, -v215, v25, v30
	v_fma_f32 v30, -v216, v26, v30
	v_fma_f32 v27, -v27, v217, v30
	ds_read_b128 v[202:205], v5 offset:26208
	s_waitcnt lgkmcnt(9)
	v_fma_f32 v28, -v16, v228, v28
	v_fma_f32 v28, -v17, v229, v28
	v_fma_f32 v28, -v18, v230, v28
	v_fma_f32 v28, -v19, v231, v28
	ds_read_b128 v[206:209], v5 offset:26224
	s_waitcnt lgkmcnt(9)
	v_fma_f32 v28, -v20, v232, v28
	v_fma_f32 v28, -v21, v233, v28
	v_fma_f32 v28, -v234, v22, v28
	v_fma_f32 v28, -v235, v23, v28
	ds_read_b128 v[214:217], v5 offset:26432
	s_waitcnt lgkmcnt(9)
	v_fma_f32 v28, -v244, v24, v28
	v_fma_f32 v28, -v245, v25, v28
	v_fma_f32 v28, -v246, v26, v28
	v_fma_f32 v28, -v247, v27, v28
	ds_read_b128 v[228:231], v5 offset:26448
	s_waitcnt lgkmcnt(9)
	v_fma_f32 v30, -v16, v178, v29
	v_fma_f32 v30, -v17, v179, v30
	v_fma_f32 v30, -v18, v180, v30
	v_fma_f32 v30, -v19, v181, v30
	ds_read_b128 v[232:235], v5 offset:26464
	s_waitcnt lgkmcnt(9)
	v_fma_f32 v30, -v20, v182, v30
	v_fma_f32 v30, -v21, v183, v30
	v_fma_f32 v30, -v22, v184, v30
	v_fma_f32 v30, -v185, v23, v30
	ds_read_b128 v[244:247], v5 offset:26480
	s_waitcnt lgkmcnt(9)
	v_fma_f32 v30, -v186, v24, v30
	v_fma_f32 v30, -v187, v25, v30
	v_fma_f32 v30, -v188, v26, v30
	v_fma_f32 v30, -v189, v27, v30
	ds_read_b128 v[178:181], v5 offset:26688
	s_waitcnt lgkmcnt(9)
	v_fma_f32 v30, -v190, v28, v30
	v_fma_f32 v29, -v29, v191, v30
	v_fma_f32 v29, -v72, v192, v29
	v_fma_f32 v29, -v32, v193, v29
	ds_read_b128 v[182:185], v5 offset:26704
	s_waitcnt lgkmcnt(9)
	v_fma_f32 v30, -v16, v194, v72
	v_fma_f32 v30, -v17, v195, v30
	v_fma_f32 v30, -v18, v196, v30
	v_fma_f32 v30, -v19, v197, v30
	ds_read_b128 v[186:189], v5 offset:26720
	s_waitcnt lgkmcnt(9)
	v_fma_f32 v30, -v20, v198, v30
	v_fma_f32 v30, -v21, v199, v30
	v_fma_f32 v30, -v22, v200, v30
	v_fma_f32 v30, -v23, v201, v30
	ds_read_b128 v[190:193], v5 offset:26736
	s_waitcnt lgkmcnt(9)
	v_fma_f32 v30, -v24, v202, v30
	v_fma_f32 v30, -v203, v25, v30
	v_fma_f32 v30, -v204, v26, v30
	v_fma_f32 v30, -v205, v27, v30
	ds_read_b128 v[194:197], v5 offset:26960
	s_waitcnt lgkmcnt(9)
	v_fma_f32 v30, -v206, v28, v30
	v_fma_f32 v30, -v207, v29, v30
	v_fma_f32 v30, -v72, v208, v30
	v_fma_f32 v30, -v32, v209, v30
	ds_read_b128 v[198:201], v5 offset:26944
	s_waitcnt lgkmcnt(9)
	v_fma_f32 v31, -v16, v214, v32
	v_fma_f32 v31, -v17, v215, v31
	v_fma_f32 v31, -v18, v216, v31
	v_fma_f32 v31, -v19, v217, v31
	ds_read_b128 v[202:205], v5 offset:26992
	s_waitcnt lgkmcnt(9)
	v_fma_f32 v31, -v20, v228, v31
	v_fma_f32 v31, -v21, v229, v31
	v_fma_f32 v31, -v22, v230, v31
	v_fma_f32 v31, -v23, v231, v31
	ds_read_b128 v[206:209], v5 offset:26976
	s_waitcnt lgkmcnt(9)
	v_fma_f32 v31, -v24, v232, v31
	v_fma_f32 v31, -v25, v233, v31
	v_fma_f32 v31, -v234, v26, v31
	v_fma_f32 v31, -v235, v27, v31
	ds_read_b128 v[214:217], v5 offset:27200
	s_waitcnt lgkmcnt(9)
	v_fma_f32 v31, -v244, v28, v31
	v_fma_f32 v31, -v245, v29, v31
	v_fma_f32 v31, -v246, v30, v31
	v_fma_f32 v31, -v32, v247, v31
	ds_read_b128 v[228:231], v5 offset:27216
	s_waitcnt lgkmcnt(9)
	v_pk_fma_f32 v[210:211], v[16:17], v[178:179], 0
	v_pk_fma_f32 v[210:211], v[18:19], v[180:181], v[210:211]
	ds_read_b128 v[232:235], v5 offset:27232
	s_waitcnt lgkmcnt(9)
	v_pk_fma_f32 v[210:211], v[20:21], v[182:183], v[210:211]
	v_pk_fma_f32 v[210:211], v[22:23], v[184:185], v[210:211]
	ds_read_b128 v[244:247], v5 offset:27248
	s_waitcnt lgkmcnt(9)
	v_pk_fma_f32 v[210:211], v[24:25], v[186:187], v[210:211]
	v_pk_fma_f32 v[210:211], v[26:27], v[188:189], v[210:211]
	ds_read_b128 v[178:181], v5 offset:27472
	s_waitcnt lgkmcnt(9)
	v_pk_fma_f32 v[210:211], v[28:29], v[190:191], v[210:211]
	v_pk_fma_f32 v[210:211], v[30:31], v[192:193], v[210:211]
	ds_read_b128 v[182:185], v5 offset:27456
	v_add_f32_e32 v32, v210, v211
	v_sub_f32_e32 v32, v33, v32
	s_waitcnt lgkmcnt(8)
	v_pk_fma_f32 v[218:219], v[16:17], v[198:199], 0
	v_pk_fma_f32 v[218:219], v[18:19], v[200:201], v[218:219]
	ds_read_b128 v[186:189], v5 offset:27504
	v_pk_fma_f32 v[218:219], v[20:21], v[194:195], v[218:219]
	v_pk_fma_f32 v[218:219], v[22:23], v[196:197], v[218:219]
	ds_read_b128 v[190:193], v5 offset:27488
	s_waitcnt lgkmcnt(8)
	v_pk_fma_f32 v[218:219], v[24:25], v[206:207], v[218:219]
	v_pk_fma_f32 v[218:219], v[26:27], v[208:209], v[218:219]
	ds_read_b128 v[198:201], v5 offset:27712
	v_pk_fma_f32 v[218:219], v[28:29], v[202:203], v[218:219]
	v_pk_fma_f32 v[218:219], v[30:31], v[204:205], v[218:219]
	ds_read_b128 v[194:197], v5 offset:27728
	v_add_f32_e32 v33, v218, v219
	v_sub_f32_e32 v33, v34, v33
	s_waitcnt lgkmcnt(9)
	v_pk_fma_f32 v[236:237], v[16:17], v[214:215], 0
	v_pk_fma_f32 v[236:237], v[18:19], v[216:217], v[236:237]
	ds_read_b128 v[206:209], v5 offset:27744
	s_waitcnt lgkmcnt(9)
	v_pk_fma_f32 v[236:237], v[20:21], v[228:229], v[236:237]
	v_pk_fma_f32 v[236:237], v[22:23], v[230:231], v[236:237]
	ds_read_b128 v[202:205], v5 offset:27760
	s_waitcnt lgkmcnt(9)
	v_pk_fma_f32 v[236:237], v[24:25], v[232:233], v[236:237]
	v_pk_fma_f32 v[236:237], v[26:27], v[234:235], v[236:237]
	ds_read_b128 v[214:217], v5 offset:27984
	s_waitcnt lgkmcnt(9)
	v_pk_fma_f32 v[236:237], v[28:29], v[244:245], v[236:237]
	v_pk_fma_f32 v[236:237], v[30:31], v[246:247], v[236:237]
	ds_read_b128 v[228:231], v5 offset:27968
	v_add_f32_e32 v34, v236, v237
	v_sub_f32_e32 v34, v35, v34
	s_waitcnt lgkmcnt(8)
	v_pk_fma_f32 v[248:249], v[16:17], v[182:183], 0
	v_pk_fma_f32 v[248:249], v[18:19], v[184:185], v[248:249]
	ds_read_b128 v[232:235], v5 offset:28016
	v_pk_fma_f32 v[248:249], v[20:21], v[178:179], v[248:249]
	v_pk_fma_f32 v[248:249], v[22:23], v[180:181], v[248:249]
	ds_read_b128 v[244:247], v5 offset:28000
	s_waitcnt lgkmcnt(8)
	v_pk_fma_f32 v[248:249], v[24:25], v[190:191], v[248:249]
	v_pk_fma_f32 v[248:249], v[26:27], v[192:193], v[248:249]
	ds_read_b128 v[182:185], v5 offset:28224
	v_pk_fma_f32 v[248:249], v[28:29], v[186:187], v[248:249]
	v_pk_fma_f32 v[248:249], v[30:31], v[188:189], v[248:249]
	ds_read_b128 v[178:181], v5 offset:28240
	v_add_f32_e32 v35, v248, v249
	v_sub_f32_e32 v35, v36, v35
	s_waitcnt lgkmcnt(9)
	v_pk_fma_f32 v[210:211], v[16:17], v[198:199], 0
	v_pk_fma_f32 v[210:211], v[18:19], v[200:201], v[210:211]
	ds_read_b128 v[190:193], v5 offset:28256
	s_waitcnt lgkmcnt(9)
	v_pk_fma_f32 v[210:211], v[20:21], v[194:195], v[210:211]
	v_pk_fma_f32 v[210:211], v[22:23], v[196:197], v[210:211]
	ds_read_b128 v[186:189], v5 offset:28272
	s_waitcnt lgkmcnt(9)
	v_pk_fma_f32 v[210:211], v[24:25], v[206:207], v[210:211]
	v_pk_fma_f32 v[210:211], v[26:27], v[208:209], v[210:211]
	ds_read_b128 v[198:201], v5 offset:28496
	s_waitcnt lgkmcnt(9)
	v_pk_fma_f32 v[210:211], v[28:29], v[202:203], v[210:211]
	v_pk_fma_f32 v[210:211], v[30:31], v[204:205], v[210:211]
	ds_read_b128 v[194:197], v5 offset:28480
	v_add_f32_e32 v36, v210, v211
	v_sub_f32_e32 v36, v37, v36
	s_waitcnt lgkmcnt(8)
	v_pk_fma_f32 v[218:219], v[16:17], v[228:229], 0
	v_pk_fma_f32 v[218:219], v[18:19], v[230:231], v[218:219]
	ds_read_b128 v[206:209], v5 offset:28528
	v_pk_fma_f32 v[218:219], v[20:21], v[214:215], v[218:219]
	v_pk_fma_f32 v[218:219], v[22:23], v[216:217], v[218:219]
	ds_read_b128 v[202:205], v5 offset:28512
	s_waitcnt lgkmcnt(8)
	v_pk_fma_f32 v[218:219], v[24:25], v[244:245], v[218:219]
	v_pk_fma_f32 v[218:219], v[26:27], v[246:247], v[218:219]
	ds_read_b128 v[228:231], v5 offset:28736
	v_pk_fma_f32 v[218:219], v[28:29], v[232:233], v[218:219]
	v_pk_fma_f32 v[218:219], v[30:31], v[234:235], v[218:219]
	ds_read_b128 v[214:217], v5 offset:28752
	v_add_f32_e32 v37, v218, v219
	v_sub_f32_e32 v37, v38, v37
	s_waitcnt lgkmcnt(9)
	v_pk_fma_f32 v[236:237], v[16:17], v[182:183], 0
	v_pk_fma_f32 v[236:237], v[18:19], v[184:185], v[236:237]
	ds_read_b128 v[244:247], v5 offset:28768
	s_waitcnt lgkmcnt(9)
	v_pk_fma_f32 v[236:237], v[20:21], v[178:179], v[236:237]
	v_pk_fma_f32 v[236:237], v[22:23], v[180:181], v[236:237]
	ds_read_b128 v[232:235], v5 offset:28784
	s_waitcnt lgkmcnt(9)
	v_pk_fma_f32 v[236:237], v[24:25], v[190:191], v[236:237]
	v_pk_fma_f32 v[236:237], v[26:27], v[192:193], v[236:237]
	ds_read_b128 v[182:185], v5 offset:29008
	s_waitcnt lgkmcnt(9)
	v_pk_fma_f32 v[236:237], v[28:29], v[186:187], v[236:237]
	v_pk_fma_f32 v[236:237], v[30:31], v[188:189], v[236:237]
	ds_read_b128 v[178:181], v5 offset:28992
	v_add_f32_e32 v38, v236, v237
	v_sub_f32_e32 v38, v39, v38
	s_waitcnt lgkmcnt(8)
	v_pk_fma_f32 v[248:249], v[16:17], v[194:195], 0
	v_pk_fma_f32 v[248:249], v[18:19], v[196:197], v[248:249]
	ds_read_b128 v[190:193], v5 offset:29040
	v_pk_fma_f32 v[248:249], v[20:21], v[198:199], v[248:249]
	v_pk_fma_f32 v[248:249], v[22:23], v[200:201], v[248:249]
	ds_read_b128 v[186:189], v5 offset:29024
	s_waitcnt lgkmcnt(8)
	v_pk_fma_f32 v[248:249], v[24:25], v[202:203], v[248:249]
	v_pk_fma_f32 v[248:249], v[26:27], v[204:205], v[248:249]
	ds_read_b128 v[194:197], v5 offset:29248
	v_pk_fma_f32 v[248:249], v[28:29], v[206:207], v[248:249]
	v_pk_fma_f32 v[248:249], v[30:31], v[208:209], v[248:249]
	ds_read_b128 v[198:201], v5 offset:29264
	v_add_f32_e32 v39, v248, v249
	v_sub_f32_e32 v39, v40, v39
	s_waitcnt lgkmcnt(9)
	v_pk_fma_f32 v[210:211], v[16:17], v[228:229], 0
	v_pk_fma_f32 v[210:211], v[18:19], v[230:231], v[210:211]
	ds_read_b128 v[202:205], v5 offset:29280
	s_waitcnt lgkmcnt(9)
	v_pk_fma_f32 v[210:211], v[20:21], v[214:215], v[210:211]
	v_pk_fma_f32 v[210:211], v[22:23], v[216:217], v[210:211]
	ds_read_b128 v[206:209], v5 offset:29296
	s_waitcnt lgkmcnt(9)
	v_pk_fma_f32 v[210:211], v[24:25], v[244:245], v[210:211]
	v_pk_fma_f32 v[210:211], v[26:27], v[246:247], v[210:211]
	ds_read_b128 v[228:231], v5 offset:29520
	s_waitcnt lgkmcnt(9)
	v_pk_fma_f32 v[210:211], v[28:29], v[232:233], v[210:211]
	v_pk_fma_f32 v[210:211], v[30:31], v[234:235], v[210:211]
	ds_read_b128 v[214:217], v5 offset:29504
	v_add_f32_e32 v40, v210, v211
	v_sub_f32_e32 v40, v41, v40
	s_waitcnt lgkmcnt(8)
	v_pk_fma_f32 v[218:219], v[16:17], v[178:179], 0
	v_pk_fma_f32 v[218:219], v[18:19], v[180:181], v[218:219]
	ds_read_b128 v[244:247], v5 offset:29552
	v_pk_fma_f32 v[218:219], v[20:21], v[182:183], v[218:219]
	v_pk_fma_f32 v[218:219], v[22:23], v[184:185], v[218:219]
	ds_read_b128 v[232:235], v5 offset:29536
	s_waitcnt lgkmcnt(8)
	v_pk_fma_f32 v[218:219], v[24:25], v[186:187], v[218:219]
	v_pk_fma_f32 v[218:219], v[26:27], v[188:189], v[218:219]
	ds_read_b128 v[178:181], v5 offset:29760
	v_pk_fma_f32 v[218:219], v[28:29], v[190:191], v[218:219]
	v_pk_fma_f32 v[218:219], v[30:31], v[192:193], v[218:219]
	ds_read_b128 v[182:185], v5 offset:29776
	v_add_f32_e32 v41, v218, v219
	v_sub_f32_e32 v41, v42, v41
	s_waitcnt lgkmcnt(9)
	v_pk_fma_f32 v[236:237], v[16:17], v[194:195], 0
	v_pk_fma_f32 v[236:237], v[18:19], v[196:197], v[236:237]
	ds_read_b128 v[186:189], v5 offset:29792
	s_waitcnt lgkmcnt(9)
	v_pk_fma_f32 v[236:237], v[20:21], v[198:199], v[236:237]
	v_pk_fma_f32 v[236:237], v[22:23], v[200:201], v[236:237]
	ds_read_b128 v[190:193], v5 offset:29808
	s_waitcnt lgkmcnt(9)
	v_pk_fma_f32 v[236:237], v[24:25], v[202:203], v[236:237]
	v_pk_fma_f32 v[236:237], v[26:27], v[204:205], v[236:237]
	ds_read_b128 v[194:197], v5 offset:30032
	s_waitcnt lgkmcnt(9)
	v_pk_fma_f32 v[236:237], v[28:29], v[206:207], v[236:237]
	v_pk_fma_f32 v[236:237], v[30:31], v[208:209], v[236:237]
	ds_read_b128 v[198:201], v5 offset:30016
	v_add_f32_e32 v42, v236, v237
	v_sub_f32_e32 v42, v43, v42
	s_waitcnt lgkmcnt(8)
	v_pk_fma_f32 v[248:249], v[16:17], v[214:215], 0
	v_pk_fma_f32 v[248:249], v[18:19], v[216:217], v[248:249]
	ds_read_b128 v[202:205], v5 offset:30064
	v_pk_fma_f32 v[248:249], v[20:21], v[228:229], v[248:249]
	v_pk_fma_f32 v[248:249], v[22:23], v[230:231], v[248:249]
	ds_read_b128 v[206:209], v5 offset:30048
	s_waitcnt lgkmcnt(8)
	v_pk_fma_f32 v[248:249], v[24:25], v[232:233], v[248:249]
	v_pk_fma_f32 v[248:249], v[26:27], v[234:235], v[248:249]
	ds_read_b128 v[214:217], v5 offset:30272
	v_pk_fma_f32 v[248:249], v[28:29], v[244:245], v[248:249]
	v_pk_fma_f32 v[248:249], v[30:31], v[246:247], v[248:249]
	ds_read_b128 v[228:231], v5 offset:30288
	v_add_f32_e32 v43, v248, v249
	v_sub_f32_e32 v43, v44, v43
	s_waitcnt lgkmcnt(9)
	v_pk_fma_f32 v[210:211], v[16:17], v[178:179], 0
	v_pk_fma_f32 v[210:211], v[18:19], v[180:181], v[210:211]
	ds_read_b128 v[232:235], v5 offset:30304
	s_waitcnt lgkmcnt(9)
	v_pk_fma_f32 v[210:211], v[20:21], v[182:183], v[210:211]
	v_pk_fma_f32 v[210:211], v[22:23], v[184:185], v[210:211]
	ds_read_b128 v[244:247], v5 offset:30320
	s_waitcnt lgkmcnt(9)
	v_pk_fma_f32 v[210:211], v[24:25], v[186:187], v[210:211]
	v_pk_fma_f32 v[210:211], v[26:27], v[188:189], v[210:211]
	ds_read_b128 v[178:181], v5 offset:30544
	s_waitcnt lgkmcnt(9)
	v_pk_fma_f32 v[210:211], v[28:29], v[190:191], v[210:211]
	v_pk_fma_f32 v[210:211], v[30:31], v[192:193], v[210:211]
	ds_read_b128 v[182:185], v5 offset:30528
	v_add_f32_e32 v44, v210, v211
	v_sub_f32_e32 v44, v45, v44
	s_waitcnt lgkmcnt(8)
	v_pk_fma_f32 v[218:219], v[16:17], v[198:199], 0
	v_pk_fma_f32 v[218:219], v[18:19], v[200:201], v[218:219]
	ds_read_b128 v[186:189], v5 offset:30576
	v_pk_fma_f32 v[218:219], v[20:21], v[194:195], v[218:219]
	v_pk_fma_f32 v[218:219], v[22:23], v[196:197], v[218:219]
	ds_read_b128 v[190:193], v5 offset:30560
	s_waitcnt lgkmcnt(8)
	v_pk_fma_f32 v[218:219], v[24:25], v[206:207], v[218:219]
	v_pk_fma_f32 v[218:219], v[26:27], v[208:209], v[218:219]
	ds_read_b128 v[198:201], v5 offset:30784
	v_pk_fma_f32 v[218:219], v[28:29], v[202:203], v[218:219]
	v_pk_fma_f32 v[218:219], v[30:31], v[204:205], v[218:219]
	ds_read_b128 v[194:197], v5 offset:30800
	v_add_f32_e32 v45, v218, v219
	v_sub_f32_e32 v45, v46, v45
	s_waitcnt lgkmcnt(9)
	v_pk_fma_f32 v[236:237], v[16:17], v[214:215], 0
	v_pk_fma_f32 v[236:237], v[18:19], v[216:217], v[236:237]
	ds_read_b128 v[206:209], v5 offset:30816
	s_waitcnt lgkmcnt(9)
	v_pk_fma_f32 v[236:237], v[20:21], v[228:229], v[236:237]
	v_pk_fma_f32 v[236:237], v[22:23], v[230:231], v[236:237]
	ds_read_b128 v[202:205], v5 offset:30832
	s_waitcnt lgkmcnt(9)
	v_pk_fma_f32 v[236:237], v[24:25], v[232:233], v[236:237]
	v_pk_fma_f32 v[236:237], v[26:27], v[234:235], v[236:237]
	ds_read_b128 v[214:217], v5 offset:31056
	s_waitcnt lgkmcnt(9)
	v_pk_fma_f32 v[236:237], v[28:29], v[244:245], v[236:237]
	v_pk_fma_f32 v[236:237], v[30:31], v[246:247], v[236:237]
	ds_read_b128 v[228:231], v5 offset:31040
	v_add_f32_e32 v46, v236, v237
	v_sub_f32_e32 v46, v47, v46
	s_waitcnt lgkmcnt(8)
	v_pk_fma_f32 v[248:249], v[16:17], v[182:183], 0
	v_pk_fma_f32 v[248:249], v[18:19], v[184:185], v[248:249]
	ds_read_b128 v[232:235], v5 offset:31088
	v_pk_fma_f32 v[248:249], v[20:21], v[178:179], v[248:249]
	v_pk_fma_f32 v[248:249], v[22:23], v[180:181], v[248:249]
	ds_read_b128 v[244:247], v5 offset:31072
	s_waitcnt lgkmcnt(8)
	v_pk_fma_f32 v[248:249], v[24:25], v[190:191], v[248:249]
	v_pk_fma_f32 v[248:249], v[26:27], v[192:193], v[248:249]
	ds_read_b128 v[182:185], v5 offset:31296
	v_pk_fma_f32 v[248:249], v[28:29], v[186:187], v[248:249]
	v_pk_fma_f32 v[248:249], v[30:31], v[188:189], v[248:249]
	ds_read_b128 v[178:181], v5 offset:31312
	v_add_f32_e32 v47, v248, v249
	v_sub_f32_e32 v47, v48, v47
	s_waitcnt lgkmcnt(9)
	v_pk_fma_f32 v[210:211], v[16:17], v[198:199], 0
	v_pk_fma_f32 v[210:211], v[18:19], v[200:201], v[210:211]
	ds_read_b128 v[190:193], v5 offset:31328
	s_waitcnt lgkmcnt(9)
	v_pk_fma_f32 v[210:211], v[20:21], v[194:195], v[210:211]
	v_pk_fma_f32 v[210:211], v[22:23], v[196:197], v[210:211]
	ds_read_b128 v[186:189], v5 offset:31344
	s_waitcnt lgkmcnt(9)
	v_pk_fma_f32 v[210:211], v[24:25], v[206:207], v[210:211]
	v_pk_fma_f32 v[210:211], v[26:27], v[208:209], v[210:211]
	ds_read_b128 v[198:201], v5 offset:31568
	s_waitcnt lgkmcnt(9)
	v_pk_fma_f32 v[210:211], v[28:29], v[202:203], v[210:211]
	v_pk_fma_f32 v[210:211], v[30:31], v[204:205], v[210:211]
	ds_read_b128 v[194:197], v5 offset:31552
	v_add_f32_e32 v48, v210, v211
	v_sub_f32_e32 v48, v49, v48
	s_waitcnt lgkmcnt(8)
	v_pk_fma_f32 v[218:219], v[16:17], v[228:229], 0
	v_pk_fma_f32 v[218:219], v[18:19], v[230:231], v[218:219]
	ds_read_b128 v[206:209], v5 offset:31600
	v_pk_fma_f32 v[218:219], v[20:21], v[214:215], v[218:219]
	v_pk_fma_f32 v[218:219], v[22:23], v[216:217], v[218:219]
	ds_read_b128 v[202:205], v5 offset:31584
	s_waitcnt lgkmcnt(8)
	v_pk_fma_f32 v[218:219], v[24:25], v[244:245], v[218:219]
	v_pk_fma_f32 v[218:219], v[26:27], v[246:247], v[218:219]
	ds_read_b128 v[228:231], v5 offset:31808
	v_pk_fma_f32 v[218:219], v[28:29], v[232:233], v[218:219]
	v_pk_fma_f32 v[218:219], v[30:31], v[234:235], v[218:219]
	ds_read_b128 v[214:217], v5 offset:31824
	v_add_f32_e32 v49, v218, v219
	v_sub_f32_e32 v49, v50, v49
	s_waitcnt lgkmcnt(9)
	v_pk_fma_f32 v[236:237], v[16:17], v[182:183], 0
	v_pk_fma_f32 v[236:237], v[18:19], v[184:185], v[236:237]
	ds_read_b128 v[244:247], v5 offset:31840
	s_waitcnt lgkmcnt(9)
	v_pk_fma_f32 v[236:237], v[20:21], v[178:179], v[236:237]
	v_pk_fma_f32 v[236:237], v[22:23], v[180:181], v[236:237]
	ds_read_b128 v[232:235], v5 offset:31856
	s_waitcnt lgkmcnt(9)
	v_pk_fma_f32 v[236:237], v[24:25], v[190:191], v[236:237]
	v_pk_fma_f32 v[236:237], v[26:27], v[192:193], v[236:237]
	ds_read_b128 v[182:185], v5 offset:32080
	s_waitcnt lgkmcnt(9)
	v_pk_fma_f32 v[236:237], v[28:29], v[186:187], v[236:237]
	v_pk_fma_f32 v[236:237], v[30:31], v[188:189], v[236:237]
	ds_read_b128 v[178:181], v5 offset:32064
	v_add_f32_e32 v50, v236, v237
	v_sub_f32_e32 v50, v51, v50
	s_waitcnt lgkmcnt(8)
	v_pk_fma_f32 v[248:249], v[16:17], v[194:195], 0
	v_pk_fma_f32 v[248:249], v[18:19], v[196:197], v[248:249]
	ds_read_b128 v[190:193], v5 offset:32112
	v_pk_fma_f32 v[248:249], v[20:21], v[198:199], v[248:249]
	v_pk_fma_f32 v[248:249], v[22:23], v[200:201], v[248:249]
	ds_read_b128 v[186:189], v5 offset:32096
	s_waitcnt lgkmcnt(8)
	v_pk_fma_f32 v[248:249], v[24:25], v[202:203], v[248:249]
	v_pk_fma_f32 v[248:249], v[26:27], v[204:205], v[248:249]
	ds_read_b128 v[194:197], v5 offset:32320
	v_pk_fma_f32 v[248:249], v[28:29], v[206:207], v[248:249]
	v_pk_fma_f32 v[248:249], v[30:31], v[208:209], v[248:249]
	ds_read_b128 v[198:201], v5 offset:32336
	v_add_f32_e32 v51, v248, v249
	v_sub_f32_e32 v51, v52, v51
	s_waitcnt lgkmcnt(9)
	v_pk_fma_f32 v[210:211], v[16:17], v[228:229], 0
	v_pk_fma_f32 v[210:211], v[18:19], v[230:231], v[210:211]
	ds_read_b128 v[202:205], v5 offset:32352
	s_waitcnt lgkmcnt(9)
	v_pk_fma_f32 v[210:211], v[20:21], v[214:215], v[210:211]
	v_pk_fma_f32 v[210:211], v[22:23], v[216:217], v[210:211]
	ds_read_b128 v[206:209], v5 offset:32368
	s_waitcnt lgkmcnt(9)
	v_pk_fma_f32 v[210:211], v[24:25], v[244:245], v[210:211]
	v_pk_fma_f32 v[210:211], v[26:27], v[246:247], v[210:211]
	ds_read_b128 v[228:231], v5 offset:32592
	s_waitcnt lgkmcnt(9)
	v_pk_fma_f32 v[210:211], v[28:29], v[232:233], v[210:211]
	v_pk_fma_f32 v[210:211], v[30:31], v[234:235], v[210:211]
	ds_read_b128 v[214:217], v5 offset:32576
	v_add_f32_e32 v52, v210, v211
	v_sub_f32_e32 v52, v53, v52
	s_waitcnt lgkmcnt(8)
	v_pk_fma_f32 v[218:219], v[16:17], v[178:179], 0
	v_pk_fma_f32 v[218:219], v[18:19], v[180:181], v[218:219]
	ds_read_b128 v[244:247], v5 offset:32624
	v_pk_fma_f32 v[218:219], v[20:21], v[182:183], v[218:219]
	v_pk_fma_f32 v[218:219], v[22:23], v[184:185], v[218:219]
	ds_read_b128 v[232:235], v5 offset:32608
	s_waitcnt lgkmcnt(8)
	v_pk_fma_f32 v[218:219], v[24:25], v[186:187], v[218:219]
	v_pk_fma_f32 v[218:219], v[26:27], v[188:189], v[218:219]
	ds_read_b128 v[178:181], v5 offset:32832
	v_pk_fma_f32 v[218:219], v[28:29], v[190:191], v[218:219]
	v_pk_fma_f32 v[218:219], v[30:31], v[192:193], v[218:219]
	ds_read_b128 v[182:185], v5 offset:32848
	v_add_f32_e32 v53, v218, v219
	v_sub_f32_e32 v53, v54, v53
	s_waitcnt lgkmcnt(9)
	v_pk_fma_f32 v[236:237], v[16:17], v[194:195], 0
	v_pk_fma_f32 v[236:237], v[18:19], v[196:197], v[236:237]
	ds_read_b128 v[186:189], v5 offset:32864
	s_waitcnt lgkmcnt(9)
	v_pk_fma_f32 v[236:237], v[20:21], v[198:199], v[236:237]
	v_pk_fma_f32 v[236:237], v[22:23], v[200:201], v[236:237]
	ds_read_b128 v[190:193], v5 offset:32880
	s_waitcnt lgkmcnt(9)
	v_pk_fma_f32 v[236:237], v[24:25], v[202:203], v[236:237]
	v_pk_fma_f32 v[236:237], v[26:27], v[204:205], v[236:237]
	ds_read_b128 v[194:197], v5 offset:33104
	s_waitcnt lgkmcnt(9)
	v_pk_fma_f32 v[236:237], v[28:29], v[206:207], v[236:237]
	v_pk_fma_f32 v[236:237], v[30:31], v[208:209], v[236:237]
	ds_read_b128 v[198:201], v5 offset:33088
	v_add_f32_e32 v54, v236, v237
	v_sub_f32_e32 v54, v55, v54
	s_waitcnt lgkmcnt(8)
	v_pk_fma_f32 v[248:249], v[16:17], v[214:215], 0
	v_pk_fma_f32 v[248:249], v[18:19], v[216:217], v[248:249]
	ds_read_b128 v[202:205], v5 offset:33136
	v_pk_fma_f32 v[248:249], v[20:21], v[228:229], v[248:249]
	v_pk_fma_f32 v[248:249], v[22:23], v[230:231], v[248:249]
	ds_read_b128 v[206:209], v5 offset:33120
	s_waitcnt lgkmcnt(8)
	v_pk_fma_f32 v[248:249], v[24:25], v[232:233], v[248:249]
	v_pk_fma_f32 v[248:249], v[26:27], v[234:235], v[248:249]
	ds_read_b128 v[214:217], v5 offset:33344
	v_pk_fma_f32 v[248:249], v[28:29], v[244:245], v[248:249]
	v_pk_fma_f32 v[248:249], v[30:31], v[246:247], v[248:249]
	ds_read_b128 v[228:231], v5 offset:33360
	v_add_f32_e32 v55, v248, v249
	v_sub_f32_e32 v55, v56, v55
	s_waitcnt lgkmcnt(9)
	v_pk_fma_f32 v[210:211], v[16:17], v[178:179], 0
	v_pk_fma_f32 v[210:211], v[18:19], v[180:181], v[210:211]
	ds_read_b128 v[232:235], v5 offset:33376
	s_waitcnt lgkmcnt(9)
	v_pk_fma_f32 v[210:211], v[20:21], v[182:183], v[210:211]
	v_pk_fma_f32 v[210:211], v[22:23], v[184:185], v[210:211]
	ds_read_b128 v[244:247], v5 offset:33392
	s_waitcnt lgkmcnt(9)
	v_pk_fma_f32 v[210:211], v[24:25], v[186:187], v[210:211]
	v_pk_fma_f32 v[210:211], v[26:27], v[188:189], v[210:211]
	ds_read_b128 v[178:181], v5 offset:33616
	s_waitcnt lgkmcnt(9)
	v_pk_fma_f32 v[210:211], v[28:29], v[190:191], v[210:211]
	v_pk_fma_f32 v[210:211], v[30:31], v[192:193], v[210:211]
	ds_read_b128 v[182:185], v5 offset:33600
	v_add_f32_e32 v56, v210, v211
	v_sub_f32_e32 v56, v57, v56
	s_waitcnt lgkmcnt(8)
	v_pk_fma_f32 v[218:219], v[16:17], v[198:199], 0
	v_pk_fma_f32 v[218:219], v[18:19], v[200:201], v[218:219]
	ds_read_b128 v[186:189], v5 offset:33648
	v_pk_fma_f32 v[218:219], v[20:21], v[194:195], v[218:219]
	v_pk_fma_f32 v[218:219], v[22:23], v[196:197], v[218:219]
	ds_read_b128 v[190:193], v5 offset:33632
	s_waitcnt lgkmcnt(8)
	v_pk_fma_f32 v[218:219], v[24:25], v[206:207], v[218:219]
	v_pk_fma_f32 v[218:219], v[26:27], v[208:209], v[218:219]
	ds_read_b128 v[198:201], v5 offset:33856
	v_pk_fma_f32 v[218:219], v[28:29], v[202:203], v[218:219]
	v_pk_fma_f32 v[218:219], v[30:31], v[204:205], v[218:219]
	ds_read_b128 v[194:197], v5 offset:33872
	v_add_f32_e32 v57, v218, v219
	v_sub_f32_e32 v57, v58, v57
	s_waitcnt lgkmcnt(9)
	v_pk_fma_f32 v[236:237], v[16:17], v[214:215], 0
	v_pk_fma_f32 v[236:237], v[18:19], v[216:217], v[236:237]
	ds_read_b128 v[206:209], v5 offset:33888
	s_waitcnt lgkmcnt(9)
	v_pk_fma_f32 v[236:237], v[20:21], v[228:229], v[236:237]
	v_pk_fma_f32 v[236:237], v[22:23], v[230:231], v[236:237]
	ds_read_b128 v[202:205], v5 offset:33904
	s_waitcnt lgkmcnt(9)
	v_pk_fma_f32 v[236:237], v[24:25], v[232:233], v[236:237]
	v_pk_fma_f32 v[236:237], v[26:27], v[234:235], v[236:237]
	ds_read_b128 v[214:217], v5 offset:34128
	s_waitcnt lgkmcnt(9)
	v_pk_fma_f32 v[236:237], v[28:29], v[244:245], v[236:237]
	v_pk_fma_f32 v[236:237], v[30:31], v[246:247], v[236:237]
	ds_read_b128 v[228:231], v5 offset:34112
	v_add_f32_e32 v58, v236, v237
	v_sub_f32_e32 v58, v59, v58
	s_waitcnt lgkmcnt(8)
	v_pk_fma_f32 v[248:249], v[16:17], v[182:183], 0
	v_pk_fma_f32 v[248:249], v[18:19], v[184:185], v[248:249]
	ds_read_b128 v[232:235], v5 offset:34160
	v_pk_fma_f32 v[248:249], v[20:21], v[178:179], v[248:249]
	v_pk_fma_f32 v[248:249], v[22:23], v[180:181], v[248:249]
	ds_read_b128 v[244:247], v5 offset:34144
	s_waitcnt lgkmcnt(8)
	v_pk_fma_f32 v[248:249], v[24:25], v[190:191], v[248:249]
	v_pk_fma_f32 v[248:249], v[26:27], v[192:193], v[248:249]
	ds_read_b128 v[182:185], v5 offset:34368
	v_pk_fma_f32 v[248:249], v[28:29], v[186:187], v[248:249]
	v_pk_fma_f32 v[248:249], v[30:31], v[188:189], v[248:249]
	ds_read_b128 v[178:181], v5 offset:34384
	v_add_f32_e32 v59, v248, v249
	v_sub_f32_e32 v59, v61, v59
	s_waitcnt lgkmcnt(9)
	v_pk_fma_f32 v[210:211], v[16:17], v[198:199], 0
	v_pk_fma_f32 v[210:211], v[18:19], v[200:201], v[210:211]
	ds_read_b128 v[190:193], v5 offset:34400
	s_waitcnt lgkmcnt(9)
	v_pk_fma_f32 v[210:211], v[20:21], v[194:195], v[210:211]
	v_pk_fma_f32 v[210:211], v[22:23], v[196:197], v[210:211]
	ds_read_b128 v[186:189], v5 offset:34416
	s_waitcnt lgkmcnt(9)
	v_pk_fma_f32 v[210:211], v[24:25], v[206:207], v[210:211]
	v_pk_fma_f32 v[210:211], v[26:27], v[208:209], v[210:211]
	ds_read_b128 v[198:201], v5 offset:34640
	s_waitcnt lgkmcnt(9)
	v_pk_fma_f32 v[210:211], v[28:29], v[202:203], v[210:211]
	v_pk_fma_f32 v[210:211], v[30:31], v[204:205], v[210:211]
	ds_read_b128 v[194:197], v5 offset:34624
	v_add_f32_e32 v61, v210, v211
	v_sub_f32_e32 v61, v62, v61
	s_waitcnt lgkmcnt(8)
	v_pk_fma_f32 v[218:219], v[16:17], v[228:229], 0
	v_pk_fma_f32 v[218:219], v[18:19], v[230:231], v[218:219]
	ds_read_b128 v[206:209], v5 offset:34672
	v_pk_fma_f32 v[218:219], v[20:21], v[214:215], v[218:219]
	v_pk_fma_f32 v[218:219], v[22:23], v[216:217], v[218:219]
	ds_read_b128 v[202:205], v5 offset:34656
	s_waitcnt lgkmcnt(8)
	v_pk_fma_f32 v[218:219], v[24:25], v[244:245], v[218:219]
	v_pk_fma_f32 v[218:219], v[26:27], v[246:247], v[218:219]
	ds_read_b128 v[228:231], v5 offset:27008
	v_pk_fma_f32 v[218:219], v[28:29], v[232:233], v[218:219]
	v_pk_fma_f32 v[218:219], v[30:31], v[234:235], v[218:219]
	ds_read_b128 v[214:217], v5 offset:27264
	v_add_f32_e32 v62, v218, v219
	v_sub_f32_e32 v62, v63, v62
	s_waitcnt lgkmcnt(9)
	v_pk_fma_f32 v[236:237], v[16:17], v[182:183], 0
	v_pk_fma_f32 v[236:237], v[18:19], v[184:185], v[236:237]
	ds_read_b128 v[244:247], v5 offset:27520
	s_waitcnt lgkmcnt(9)
	v_pk_fma_f32 v[236:237], v[20:21], v[178:179], v[236:237]
	v_pk_fma_f32 v[236:237], v[22:23], v[180:181], v[236:237]
	ds_read_b128 v[232:235], v5 offset:27776
	s_waitcnt lgkmcnt(9)
	v_pk_fma_f32 v[236:237], v[24:25], v[190:191], v[236:237]
	v_pk_fma_f32 v[236:237], v[26:27], v[192:193], v[236:237]
	ds_read_b128 v[182:185], v5 offset:28032
	s_waitcnt lgkmcnt(9)
	v_pk_fma_f32 v[236:237], v[28:29], v[186:187], v[236:237]
	v_pk_fma_f32 v[236:237], v[30:31], v[188:189], v[236:237]
	ds_read_b128 v[178:181], v5 offset:28048
	v_add_f32_e32 v63, v236, v237
	v_sub_f32_e32 v63, v70, v63
	s_waitcnt lgkmcnt(8)
	v_pk_fma_f32 v[248:249], v[16:17], v[194:195], 0
	v_pk_fma_f32 v[248:249], v[18:19], v[196:197], v[248:249]
	ds_read_b128 v[190:193], v5 offset:28288
	v_pk_fma_f32 v[248:249], v[20:21], v[198:199], v[248:249]
	v_pk_fma_f32 v[248:249], v[22:23], v[200:201], v[248:249]
	ds_read_b128 v[186:189], v5 offset:28304
	s_waitcnt lgkmcnt(8)
	v_pk_fma_f32 v[248:249], v[24:25], v[202:203], v[248:249]
	v_pk_fma_f32 v[248:249], v[26:27], v[204:205], v[248:249]
	ds_read_b128 v[194:197], v5 offset:28544
	v_pk_fma_f32 v[248:249], v[28:29], v[206:207], v[248:249]
	v_pk_fma_f32 v[248:249], v[30:31], v[208:209], v[248:249]
	ds_read_b128 v[198:201], v5 offset:28560
	v_add_f32_e32 v70, v248, v249
	v_sub_f32_e32 v70, v71, v70
	s_waitcnt lgkmcnt(9)
	v_fma_f32 v71, -v32, v228, v33
	v_fma_f32 v33, -v33, v229, v71
	v_fma_f32 v33, -v34, v230, v33
	v_fma_f32 v33, -v35, v231, v33
	ds_read_b128 v[202:205], v5 offset:28800
	s_waitcnt lgkmcnt(9)
	v_fma_f32 v71, -v32, v214, v34
	v_fma_f32 v71, -v215, v33, v71
	v_fma_f32 v34, -v34, v216, v71
	v_fma_f32 v34, -v35, v217, v34
	ds_read_b128 v[206:209], v5 offset:28816
	s_waitcnt lgkmcnt(9)
	v_fma_f32 v71, -v32, v244, v35
	v_fma_f32 v71, -v245, v33, v71
	v_fma_f32 v71, -v246, v34, v71
	v_fma_f32 v35, -v35, v247, v71
	ds_read_b128 v[228:231], v5 offset:29056
	s_waitcnt lgkmcnt(9)
	v_fma_f32 v36, -v32, v232, v36
	v_fma_f32 v36, -v233, v33, v36
	v_fma_f32 v36, -v234, v34, v36
	v_fma_f32 v36, -v235, v35, v36
	ds_read_b128 v[214:217], v5 offset:29072
	s_waitcnt lgkmcnt(9)
	v_fma_f32 v71, -v32, v182, v37
	v_fma_f32 v71, -v183, v33, v71
	v_fma_f32 v71, -v184, v34, v71
	v_fma_f32 v71, -v185, v35, v71
	ds_read_b128 v[244:247], v5 offset:29088
	s_waitcnt lgkmcnt(9)
	v_fma_f32 v71, -v178, v36, v71
	v_fma_f32 v37, -v37, v179, v71
	v_fma_f32 v37, -v38, v180, v37
	v_fma_f32 v37, -v39, v181, v37
	ds_read_b128 v[232:235], v5 offset:29312
	s_waitcnt lgkmcnt(9)
	v_fma_f32 v71, -v32, v190, v38
	v_fma_f32 v71, -v33, v191, v71
	v_fma_f32 v71, -v192, v34, v71
	v_fma_f32 v71, -v193, v35, v71
	ds_read_b128 v[182:185], v5 offset:29328
	s_waitcnt lgkmcnt(9)
	v_fma_f32 v71, -v186, v36, v71
	v_fma_f32 v71, -v187, v37, v71
	v_fma_f32 v38, -v38, v188, v71
	v_fma_f32 v38, -v39, v189, v38
	ds_read_b128 v[178:181], v5 offset:29344
	s_waitcnt lgkmcnt(9)
	v_fma_f32 v71, -v32, v194, v39
	v_fma_f32 v71, -v33, v195, v71
	v_fma_f32 v71, -v196, v34, v71
	v_fma_f32 v71, -v197, v35, v71
	ds_read_b128 v[190:193], v5 offset:29568
	s_waitcnt lgkmcnt(9)
	v_fma_f32 v71, -v198, v36, v71
	v_fma_f32 v71, -v199, v37, v71
	v_fma_f32 v71, -v200, v38, v71
	v_fma_f32 v39, -v39, v201, v71
	ds_read_b128 v[186:189], v5 offset:29584
	s_waitcnt lgkmcnt(9)
	v_fma_f32 v40, -v32, v202, v40
	v_fma_f32 v40, -v33, v203, v40
	v_fma_f32 v40, -v34, v204, v40
	v_fma_f32 v40, -v205, v35, v40
	ds_read_b128 v[194:197], v5 offset:29600
	s_waitcnt lgkmcnt(9)
	v_fma_f32 v40, -v206, v36, v40
	v_fma_f32 v40, -v207, v37, v40
	v_fma_f32 v40, -v208, v38, v40
	v_fma_f32 v40, -v209, v39, v40
	ds_read_b128 v[198:201], v5 offset:29824
	s_waitcnt lgkmcnt(9)
	v_fma_f32 v71, -v32, v228, v41
	v_fma_f32 v71, -v33, v229, v71
	v_fma_f32 v71, -v34, v230, v71
	v_fma_f32 v71, -v231, v35, v71
	ds_read_b128 v[202:205], v5 offset:29840
	s_waitcnt lgkmcnt(9)
	v_fma_f32 v71, -v214, v36, v71
	v_fma_f32 v71, -v215, v37, v71
	v_fma_f32 v71, -v216, v38, v71
	v_fma_f32 v71, -v217, v39, v71
	ds_read_b128 v[206:209], v5 offset:29856
	s_waitcnt lgkmcnt(9)
	v_fma_f32 v71, -v244, v40, v71
	v_fma_f32 v41, -v41, v245, v71
	v_fma_f32 v41, -v42, v246, v41
	v_fma_f32 v41, -v43, v247, v41
	ds_read_b128 v[228:231], v5 offset:30080
	s_waitcnt lgkmcnt(9)
	v_fma_f32 v71, -v32, v232, v42
	v_fma_f32 v71, -v33, v233, v71
	v_fma_f32 v71, -v34, v234, v71
	v_fma_f32 v71, -v35, v235, v71
	ds_read_b128 v[214:217], v5 offset:30096
	s_waitcnt lgkmcnt(9)
	v_fma_f32 v71, -v36, v182, v71
	v_fma_f32 v71, -v183, v37, v71
	v_fma_f32 v71, -v184, v38, v71
	v_fma_f32 v71, -v185, v39, v71
	ds_read_b128 v[244:247], v5 offset:30112
	s_waitcnt lgkmcnt(9)
	v_fma_f32 v71, -v178, v40, v71
	v_fma_f32 v71, -v179, v41, v71
	v_fma_f32 v42, -v42, v180, v71
	v_fma_f32 v42, -v43, v181, v42
	ds_read_b128 v[232:235], v5 offset:30128
	s_waitcnt lgkmcnt(9)
	v_fma_f32 v71, -v32, v190, v43
	v_fma_f32 v71, -v33, v191, v71
	v_fma_f32 v71, -v34, v192, v71
	v_fma_f32 v71, -v35, v193, v71
	ds_read_b128 v[182:185], v5 offset:30336
	s_waitcnt lgkmcnt(9)
	v_fma_f32 v71, -v36, v186, v71
	v_fma_f32 v71, -v187, v37, v71
	v_fma_f32 v71, -v188, v38, v71
	v_fma_f32 v71, -v189, v39, v71
	ds_read_b128 v[178:181], v5 offset:30352
	s_waitcnt lgkmcnt(9)
	v_fma_f32 v71, -v194, v40, v71
	v_fma_f32 v71, -v195, v41, v71
	v_fma_f32 v71, -v196, v42, v71
	v_fma_f32 v43, -v43, v197, v71
	ds_read_b128 v[190:193], v5 offset:30368
	s_waitcnt lgkmcnt(9)
	v_fma_f32 v44, -v32, v198, v44
	v_fma_f32 v44, -v33, v199, v44
	v_fma_f32 v44, -v34, v200, v44
	v_fma_f32 v44, -v35, v201, v44
	ds_read_b128 v[186:189], v5 offset:30384
	s_waitcnt lgkmcnt(9)
	v_fma_f32 v44, -v36, v202, v44
	v_fma_f32 v44, -v37, v203, v44
	v_fma_f32 v44, -v204, v38, v44
	v_fma_f32 v44, -v205, v39, v44
	ds_read_b128 v[194:197], v5 offset:30592
	s_waitcnt lgkmcnt(9)
	v_fma_f32 v44, -v206, v40, v44
	v_fma_f32 v44, -v207, v41, v44
	v_fma_f32 v44, -v208, v42, v44
	v_fma_f32 v44, -v209, v43, v44
	ds_read_b128 v[198:201], v5 offset:30608
	s_waitcnt lgkmcnt(9)
	v_fma_f32 v71, -v32, v228, v45
	v_fma_f32 v71, -v33, v229, v71
	v_fma_f32 v71, -v34, v230, v71
	v_fma_f32 v71, -v35, v231, v71
	ds_read_b128 v[202:205], v5 offset:30624
	s_waitcnt lgkmcnt(9)
	v_fma_f32 v71, -v36, v214, v71
	v_fma_f32 v71, -v37, v215, v71
	v_fma_f32 v71, -v38, v216, v71
	v_fma_f32 v71, -v217, v39, v71
	ds_read_b128 v[206:209], v5 offset:30640
	s_waitcnt lgkmcnt(9)
	v_fma_f32 v71, -v244, v40, v71
	v_fma_f32 v71, -v245, v41, v71
	v_fma_f32 v71, -v246, v42, v71
	v_fma_f32 v71, -v247, v43, v71
	ds_read_b128 v[228:231], v5 offset:30848
	s_waitcnt lgkmcnt(9)
	v_fma_f32 v71, -v232, v44, v71
	v_fma_f32 v45, -v45, v233, v71
	v_fma_f32 v45, -v46, v234, v45
	v_fma_f32 v45, -v47, v235, v45
	ds_read_b128 v[214:217], v5 offset:30864
	s_waitcnt lgkmcnt(9)
	v_fma_f32 v71, -v32, v182, v46
	v_fma_f32 v71, -v33, v183, v71
	v_fma_f32 v71, -v34, v184, v71
	v_fma_f32 v71, -v35, v185, v71
	ds_read_b128 v[244:247], v5 offset:30880
	s_waitcnt lgkmcnt(9)
	v_fma_f32 v71, -v36, v178, v71
	v_fma_f32 v71, -v37, v179, v71
	v_fma_f32 v71, -v38, v180, v71
	v_fma_f32 v71, -v39, v181, v71
	ds_read_b128 v[232:235], v5 offset:30896
	s_waitcnt lgkmcnt(9)
	v_fma_f32 v71, -v40, v190, v71
	v_fma_f32 v71, -v191, v41, v71
	v_fma_f32 v71, -v192, v42, v71
	v_fma_f32 v71, -v193, v43, v71
	ds_read_b128 v[182:185], v5 offset:31120
	s_waitcnt lgkmcnt(9)
	v_fma_f32 v71, -v186, v44, v71
	v_fma_f32 v71, -v187, v45, v71
	v_fma_f32 v46, -v46, v188, v71
	v_fma_f32 v46, -v47, v189, v46
	ds_read_b128 v[178:181], v5 offset:31104
	s_waitcnt lgkmcnt(9)
	v_fma_f32 v71, -v32, v194, v47
	v_fma_f32 v71, -v33, v195, v71
	v_fma_f32 v71, -v34, v196, v71
	v_fma_f32 v71, -v35, v197, v71
	ds_read_b128 v[190:193], v5 offset:31152
	s_waitcnt lgkmcnt(9)
	v_fma_f32 v71, -v36, v198, v71
	v_fma_f32 v71, -v37, v199, v71
	v_fma_f32 v71, -v38, v200, v71
	v_fma_f32 v71, -v39, v201, v71
	ds_read_b128 v[186:189], v5 offset:31136
	s_waitcnt lgkmcnt(9)
	v_fma_f32 v71, -v40, v202, v71
	v_fma_f32 v71, -v41, v203, v71
	v_fma_f32 v71, -v204, v42, v71
	v_fma_f32 v71, -v205, v43, v71
	ds_read_b128 v[194:197], v5 offset:31360
	s_waitcnt lgkmcnt(9)
	v_fma_f32 v71, -v206, v44, v71
	v_fma_f32 v71, -v207, v45, v71
	v_fma_f32 v71, -v208, v46, v71
	v_fma_f32 v47, -v47, v209, v71
	ds_read_b128 v[198:201], v5 offset:31376
	s_waitcnt lgkmcnt(9)
	v_pk_fma_f32 v[210:211], v[32:33], v[228:229], 0
	v_pk_fma_f32 v[210:211], v[34:35], v[230:231], v[210:211]
	ds_read_b128 v[202:205], v5 offset:31392
	s_waitcnt lgkmcnt(9)
	v_pk_fma_f32 v[210:211], v[36:37], v[214:215], v[210:211]
	v_pk_fma_f32 v[210:211], v[38:39], v[216:217], v[210:211]
	ds_read_b128 v[206:209], v5 offset:31408
	s_waitcnt lgkmcnt(9)
	v_pk_fma_f32 v[210:211], v[40:41], v[244:245], v[210:211]
	v_pk_fma_f32 v[210:211], v[42:43], v[246:247], v[210:211]
	ds_read_b128 v[228:231], v5 offset:31632
	s_waitcnt lgkmcnt(9)
	v_pk_fma_f32 v[210:211], v[44:45], v[232:233], v[210:211]
	v_pk_fma_f32 v[210:211], v[46:47], v[234:235], v[210:211]
	ds_read_b128 v[214:217], v5 offset:31616
	v_add_f32_e32 v71, v210, v211
	v_sub_f32_e32 v48, v48, v71
	s_waitcnt lgkmcnt(8)
	v_pk_fma_f32 v[218:219], v[32:33], v[178:179], 0
	v_pk_fma_f32 v[218:219], v[34:35], v[180:181], v[218:219]
	ds_read_b128 v[244:247], v5 offset:31664
	v_pk_fma_f32 v[218:219], v[36:37], v[182:183], v[218:219]
	v_pk_fma_f32 v[218:219], v[38:39], v[184:185], v[218:219]
	ds_read_b128 v[232:235], v5 offset:31648
	s_waitcnt lgkmcnt(8)
	v_pk_fma_f32 v[218:219], v[40:41], v[186:187], v[218:219]
	v_pk_fma_f32 v[218:219], v[42:43], v[188:189], v[218:219]
	ds_read_b128 v[178:181], v5 offset:31872
	v_pk_fma_f32 v[218:219], v[44:45], v[190:191], v[218:219]
	v_pk_fma_f32 v[218:219], v[46:47], v[192:193], v[218:219]
	ds_read_b128 v[182:185], v5 offset:31888
	v_add_f32_e32 v71, v218, v219
	v_sub_f32_e32 v49, v49, v71
	s_waitcnt lgkmcnt(9)
	v_pk_fma_f32 v[236:237], v[32:33], v[194:195], 0
	v_pk_fma_f32 v[236:237], v[34:35], v[196:197], v[236:237]
	ds_read_b128 v[186:189], v5 offset:31904
	s_waitcnt lgkmcnt(9)
	v_pk_fma_f32 v[236:237], v[36:37], v[198:199], v[236:237]
	v_pk_fma_f32 v[236:237], v[38:39], v[200:201], v[236:237]
	ds_read_b128 v[190:193], v5 offset:31920
	s_waitcnt lgkmcnt(9)
	v_pk_fma_f32 v[236:237], v[40:41], v[202:203], v[236:237]
	v_pk_fma_f32 v[236:237], v[42:43], v[204:205], v[236:237]
	ds_read_b128 v[194:197], v5 offset:32144
	s_waitcnt lgkmcnt(9)
	v_pk_fma_f32 v[236:237], v[44:45], v[206:207], v[236:237]
	v_pk_fma_f32 v[236:237], v[46:47], v[208:209], v[236:237]
	ds_read_b128 v[198:201], v5 offset:32128
	v_add_f32_e32 v71, v236, v237
	v_sub_f32_e32 v50, v50, v71
	s_waitcnt lgkmcnt(8)
	v_pk_fma_f32 v[248:249], v[32:33], v[214:215], 0
	v_pk_fma_f32 v[248:249], v[34:35], v[216:217], v[248:249]
	ds_read_b128 v[202:205], v5 offset:32176
	v_pk_fma_f32 v[248:249], v[36:37], v[228:229], v[248:249]
	v_pk_fma_f32 v[248:249], v[38:39], v[230:231], v[248:249]
	ds_read_b128 v[206:209], v5 offset:32160
	s_waitcnt lgkmcnt(8)
	v_pk_fma_f32 v[248:249], v[40:41], v[232:233], v[248:249]
	v_pk_fma_f32 v[248:249], v[42:43], v[234:235], v[248:249]
	ds_read_b128 v[214:217], v5 offset:32384
	v_pk_fma_f32 v[248:249], v[44:45], v[244:245], v[248:249]
	v_pk_fma_f32 v[248:249], v[46:47], v[246:247], v[248:249]
	ds_read_b128 v[228:231], v5 offset:32400
	v_add_f32_e32 v71, v248, v249
	v_sub_f32_e32 v51, v51, v71
	s_waitcnt lgkmcnt(9)
	v_pk_fma_f32 v[210:211], v[32:33], v[178:179], 0
	v_pk_fma_f32 v[210:211], v[34:35], v[180:181], v[210:211]
	ds_read_b128 v[232:235], v5 offset:32416
	s_waitcnt lgkmcnt(9)
	v_pk_fma_f32 v[210:211], v[36:37], v[182:183], v[210:211]
	v_pk_fma_f32 v[210:211], v[38:39], v[184:185], v[210:211]
	ds_read_b128 v[244:247], v5 offset:32432
	s_waitcnt lgkmcnt(9)
	v_pk_fma_f32 v[210:211], v[40:41], v[186:187], v[210:211]
	v_pk_fma_f32 v[210:211], v[42:43], v[188:189], v[210:211]
	ds_read_b128 v[178:181], v5 offset:32656
	s_waitcnt lgkmcnt(9)
	v_pk_fma_f32 v[210:211], v[44:45], v[190:191], v[210:211]
	v_pk_fma_f32 v[210:211], v[46:47], v[192:193], v[210:211]
	ds_read_b128 v[182:185], v5 offset:32640
	v_add_f32_e32 v71, v210, v211
	v_sub_f32_e32 v52, v52, v71
	s_waitcnt lgkmcnt(8)
	v_pk_fma_f32 v[218:219], v[32:33], v[198:199], 0
	v_pk_fma_f32 v[218:219], v[34:35], v[200:201], v[218:219]
	ds_read_b128 v[186:189], v5 offset:32688
	v_pk_fma_f32 v[218:219], v[36:37], v[194:195], v[218:219]
	v_pk_fma_f32 v[218:219], v[38:39], v[196:197], v[218:219]
	ds_read_b128 v[190:193], v5 offset:32672
	s_waitcnt lgkmcnt(8)
	v_pk_fma_f32 v[218:219], v[40:41], v[206:207], v[218:219]
	v_pk_fma_f32 v[218:219], v[42:43], v[208:209], v[218:219]
	ds_read_b128 v[198:201], v5 offset:32896
	v_pk_fma_f32 v[218:219], v[44:45], v[202:203], v[218:219]
	v_pk_fma_f32 v[218:219], v[46:47], v[204:205], v[218:219]
	ds_read_b128 v[194:197], v5 offset:32912
	v_add_f32_e32 v71, v218, v219
	v_sub_f32_e32 v53, v53, v71
	s_waitcnt lgkmcnt(9)
	v_pk_fma_f32 v[236:237], v[32:33], v[214:215], 0
	v_pk_fma_f32 v[236:237], v[34:35], v[216:217], v[236:237]
	ds_read_b128 v[206:209], v5 offset:32928
	s_waitcnt lgkmcnt(9)
	v_pk_fma_f32 v[236:237], v[36:37], v[228:229], v[236:237]
	v_pk_fma_f32 v[236:237], v[38:39], v[230:231], v[236:237]
	ds_read_b128 v[202:205], v5 offset:32944
	s_waitcnt lgkmcnt(9)
	v_pk_fma_f32 v[236:237], v[40:41], v[232:233], v[236:237]
	v_pk_fma_f32 v[236:237], v[42:43], v[234:235], v[236:237]
	ds_read_b128 v[214:217], v5 offset:33168
	s_waitcnt lgkmcnt(9)
	v_pk_fma_f32 v[236:237], v[44:45], v[244:245], v[236:237]
	v_pk_fma_f32 v[236:237], v[46:47], v[246:247], v[236:237]
	ds_read_b128 v[228:231], v5 offset:33152
	v_add_f32_e32 v71, v236, v237
	v_sub_f32_e32 v77, v54, v71
	s_waitcnt lgkmcnt(8)
	v_pk_fma_f32 v[248:249], v[32:33], v[182:183], 0
	v_pk_fma_f32 v[248:249], v[34:35], v[184:185], v[248:249]
	ds_read_b128 v[232:235], v5 offset:33200
	v_pk_fma_f32 v[248:249], v[36:37], v[178:179], v[248:249]
	v_pk_fma_f32 v[248:249], v[38:39], v[180:181], v[248:249]
	ds_read_b128 v[244:247], v5 offset:33184
	s_waitcnt lgkmcnt(8)
	v_pk_fma_f32 v[248:249], v[40:41], v[190:191], v[248:249]
	v_pk_fma_f32 v[248:249], v[42:43], v[192:193], v[248:249]
	ds_read_b128 v[182:185], v5 offset:33408
	v_pk_fma_f32 v[248:249], v[44:45], v[186:187], v[248:249]
	v_pk_fma_f32 v[248:249], v[46:47], v[188:189], v[248:249]
	ds_read_b128 v[178:181], v5 offset:33424
	v_add_f32_e32 v54, v248, v249
	v_sub_f32_e32 v75, v55, v54
	s_waitcnt lgkmcnt(9)
	v_pk_fma_f32 v[210:211], v[32:33], v[198:199], 0
	v_pk_fma_f32 v[210:211], v[34:35], v[200:201], v[210:211]
	ds_read_b128 v[190:193], v5 offset:33440
	s_waitcnt lgkmcnt(9)
	v_pk_fma_f32 v[210:211], v[36:37], v[194:195], v[210:211]
	v_pk_fma_f32 v[210:211], v[38:39], v[196:197], v[210:211]
	ds_read_b128 v[186:189], v5 offset:33456
	s_waitcnt lgkmcnt(9)
	v_pk_fma_f32 v[210:211], v[40:41], v[206:207], v[210:211]
	v_pk_fma_f32 v[210:211], v[42:43], v[208:209], v[210:211]
	ds_read_b128 v[198:201], v5 offset:33680
	s_waitcnt lgkmcnt(9)
	v_pk_fma_f32 v[210:211], v[44:45], v[202:203], v[210:211]
	v_pk_fma_f32 v[210:211], v[46:47], v[204:205], v[210:211]
	ds_read_b128 v[194:197], v5 offset:33664
	v_add_f32_e32 v54, v210, v211
	v_sub_f32_e32 v76, v56, v54
	s_waitcnt lgkmcnt(8)
	v_pk_fma_f32 v[218:219], v[32:33], v[228:229], 0
	v_pk_fma_f32 v[218:219], v[34:35], v[230:231], v[218:219]
	ds_read_b128 v[206:209], v5 offset:33712
	v_pk_fma_f32 v[218:219], v[36:37], v[214:215], v[218:219]
	v_pk_fma_f32 v[218:219], v[38:39], v[216:217], v[218:219]
	ds_read_b128 v[202:205], v5 offset:33696
	s_waitcnt lgkmcnt(8)
	v_pk_fma_f32 v[218:219], v[40:41], v[244:245], v[218:219]
	v_pk_fma_f32 v[218:219], v[42:43], v[246:247], v[218:219]
	ds_read_b128 v[228:231], v5 offset:33920
	v_pk_fma_f32 v[218:219], v[44:45], v[232:233], v[218:219]
	v_pk_fma_f32 v[218:219], v[46:47], v[234:235], v[218:219]
	ds_read_b128 v[214:217], v5 offset:33936
	v_add_f32_e32 v54, v218, v219
	v_sub_f32_e32 v74, v57, v54
	s_waitcnt lgkmcnt(9)
	v_pk_fma_f32 v[236:237], v[32:33], v[182:183], 0
	v_pk_fma_f32 v[236:237], v[34:35], v[184:185], v[236:237]
	ds_read_b128 v[244:247], v5 offset:33952
	s_waitcnt lgkmcnt(9)
	v_pk_fma_f32 v[236:237], v[36:37], v[178:179], v[236:237]
	v_pk_fma_f32 v[236:237], v[38:39], v[180:181], v[236:237]
	ds_read_b128 v[232:235], v5 offset:33968
	s_waitcnt lgkmcnt(9)
	v_pk_fma_f32 v[236:237], v[40:41], v[190:191], v[236:237]
	v_pk_fma_f32 v[236:237], v[42:43], v[192:193], v[236:237]
	ds_read_b128 v[182:185], v5 offset:34192
	s_waitcnt lgkmcnt(9)
	v_pk_fma_f32 v[236:237], v[44:45], v[186:187], v[236:237]
	v_pk_fma_f32 v[236:237], v[46:47], v[188:189], v[236:237]
	ds_read_b128 v[178:181], v5 offset:34176
	v_add_f32_e32 v71, v236, v237
	v_sub_f32_e32 v73, v58, v71
	s_waitcnt lgkmcnt(8)
	v_pk_fma_f32 v[248:249], v[32:33], v[194:195], 0
	v_pk_fma_f32 v[248:249], v[34:35], v[196:197], v[248:249]
	ds_read_b128 v[190:193], v5 offset:34224
	v_pk_fma_f32 v[248:249], v[36:37], v[198:199], v[248:249]
	v_pk_fma_f32 v[248:249], v[38:39], v[200:201], v[248:249]
	ds_read_b128 v[186:189], v5 offset:34208
	s_waitcnt lgkmcnt(8)
	v_pk_fma_f32 v[248:249], v[40:41], v[202:203], v[248:249]
	v_pk_fma_f32 v[248:249], v[42:43], v[204:205], v[248:249]
	ds_read_b128 v[194:197], v5 offset:34432
	v_pk_fma_f32 v[248:249], v[44:45], v[206:207], v[248:249]
	v_pk_fma_f32 v[248:249], v[46:47], v[208:209], v[248:249]
	ds_read_b128 v[198:201], v5 offset:34448
	v_add_f32_e32 v54, v248, v249
	v_sub_f32_e32 v72, v59, v54
	s_waitcnt lgkmcnt(9)
	v_pk_fma_f32 v[210:211], v[32:33], v[228:229], 0
	v_pk_fma_f32 v[210:211], v[34:35], v[230:231], v[210:211]
	ds_read_b128 v[202:205], v5 offset:34464
	s_waitcnt lgkmcnt(9)
	v_pk_fma_f32 v[210:211], v[36:37], v[214:215], v[210:211]
	v_pk_fma_f32 v[210:211], v[38:39], v[216:217], v[210:211]
	ds_read_b128 v[206:209], v5 offset:34480
	s_waitcnt lgkmcnt(9)
	v_pk_fma_f32 v[210:211], v[40:41], v[244:245], v[210:211]
	v_pk_fma_f32 v[210:211], v[42:43], v[246:247], v[210:211]
	ds_read_b128 v[228:231], v5 offset:34704
	s_waitcnt lgkmcnt(9)
	v_pk_fma_f32 v[210:211], v[44:45], v[232:233], v[210:211]
	v_pk_fma_f32 v[210:211], v[46:47], v[234:235], v[210:211]
	ds_read_b128 v[214:217], v5 offset:34688
	ds_read_b128 v[244:247], v5 offset:34736
	ds_read_b128 v[232:235], v5 offset:34720
	v_add_f32_e32 v58, v210, v211
	v_sub_f32_e32 v71, v61, v58
	s_waitcnt lgkmcnt(10)
	v_pk_fma_f32 v[218:219], v[32:33], v[178:179], 0
	v_pk_fma_f32 v[218:219], v[34:35], v[180:181], v[218:219]
	ds_read_b128 v[178:181], v5 offset:31168
	v_pk_fma_f32 v[218:219], v[36:37], v[182:183], v[218:219]
	v_pk_fma_f32 v[218:219], v[38:39], v[184:185], v[218:219]
	ds_read_b128 v[182:185], v5 offset:31424
	s_waitcnt lgkmcnt(10)
	v_pk_fma_f32 v[218:219], v[40:41], v[186:187], v[218:219]
	v_pk_fma_f32 v[218:219], v[42:43], v[188:189], v[218:219]
	ds_read_b128 v[186:189], v5 offset:31680
	v_pk_fma_f32 v[218:219], v[44:45], v[190:191], v[218:219]
	v_pk_fma_f32 v[218:219], v[46:47], v[192:193], v[218:219]
	ds_read_b128 v[190:193], v5 offset:31936
	v_add_f32_e32 v54, v218, v219
	v_sub_f32_e32 v59, v62, v54
	s_waitcnt lgkmcnt(11)
	v_pk_fma_f32 v[236:237], v[32:33], v[194:195], 0
	v_pk_fma_f32 v[236:237], v[34:35], v[196:197], v[236:237]
	ds_read_b128 v[194:197], v5 offset:32192
	s_waitcnt lgkmcnt(11)
	v_pk_fma_f32 v[236:237], v[36:37], v[198:199], v[236:237]
	v_pk_fma_f32 v[236:237], v[38:39], v[200:201], v[236:237]
	ds_read_b128 v[198:201], v5 offset:32208
	s_waitcnt lgkmcnt(11)
	v_pk_fma_f32 v[236:237], v[40:41], v[202:203], v[236:237]
	v_pk_fma_f32 v[236:237], v[42:43], v[204:205], v[236:237]
	ds_read_b128 v[202:205], v5 offset:32448
	s_waitcnt lgkmcnt(11)
	v_pk_fma_f32 v[236:237], v[44:45], v[206:207], v[236:237]
	v_pk_fma_f32 v[236:237], v[46:47], v[208:209], v[236:237]
	ds_read_b128 v[206:209], v5 offset:32464
	v_add_f32_e32 v54, v236, v237
	v_sub_f32_e32 v57, v63, v54
	s_waitcnt lgkmcnt(10)
	v_pk_fma_f32 v[248:249], v[32:33], v[214:215], 0
	v_pk_fma_f32 v[248:249], v[34:35], v[216:217], v[248:249]
	v_pk_fma_f32 v[248:249], v[36:37], v[228:229], v[248:249]
	v_pk_fma_f32 v[248:249], v[38:39], v[230:231], v[248:249]
	ds_read_b128 v[228:231], v5 offset:32704
	s_waitcnt lgkmcnt(9)
	v_pk_fma_f32 v[248:249], v[40:41], v[232:233], v[248:249]
	v_pk_fma_f32 v[248:249], v[42:43], v[234:235], v[248:249]
	v_pk_fma_f32 v[248:249], v[44:45], v[244:245], v[248:249]
	v_pk_fma_f32 v[248:249], v[46:47], v[246:247], v[248:249]
	v_add_f32_e32 v54, v248, v249
	v_sub_f32_e32 v54, v70, v54
	s_waitcnt lgkmcnt(8)
	v_fma_f32 v55, -v48, v178, v49
	v_fma_f32 v49, -v49, v179, v55
	v_fma_f32 v49, -v50, v180, v49
	v_fma_f32 v49, -v51, v181, v49
	ds_read_b128 v[178:181], v5 offset:32720
	s_waitcnt lgkmcnt(8)
	v_fma_f32 v55, -v48, v182, v50
	v_fma_f32 v55, -v183, v49, v55
	v_fma_f32 v50, -v50, v184, v55
	v_fma_f32 v50, -v51, v185, v50
	ds_read_b128 v[182:185], v5 offset:32960
	s_waitcnt lgkmcnt(8)
	v_fma_f32 v55, -v48, v186, v51
	v_fma_f32 v55, -v187, v49, v55
	v_fma_f32 v55, -v188, v50, v55
	v_fma_f32 v51, -v51, v189, v55
	ds_read_b128 v[186:189], v5 offset:32976
	s_waitcnt lgkmcnt(8)
	v_fma_f32 v52, -v48, v190, v52
	v_fma_f32 v52, -v191, v49, v52
	v_fma_f32 v52, -v192, v50, v52
	v_fma_f32 v52, -v193, v51, v52
	ds_read_b128 v[190:193], v5 offset:33216
	s_waitcnt lgkmcnt(8)
	v_fma_f32 v55, -v48, v194, v53
	v_fma_f32 v55, -v195, v49, v55
	v_fma_f32 v55, -v196, v50, v55
	v_fma_f32 v55, -v197, v51, v55
	ds_read_b128 v[194:197], v5 offset:33232
	s_waitcnt lgkmcnt(8)
	v_fma_f32 v55, -v198, v52, v55
	v_fma_f32 v53, -v53, v199, v55
	v_fma_f32 v53, -v77, v200, v53
	v_fma_f32 v53, -v75, v201, v53
	ds_read_b128 v[198:201], v5 offset:33248
	s_waitcnt lgkmcnt(8)
	v_fma_f32 v55, -v48, v202, v77
	v_fma_f32 v55, -v49, v203, v55
	v_fma_f32 v55, -v204, v50, v55
	v_fma_f32 v55, -v205, v51, v55
	ds_read_b128 v[202:205], v5 offset:33472
	s_waitcnt lgkmcnt(8)
	v_fma_f32 v55, -v206, v52, v55
	v_fma_f32 v55, -v207, v53, v55
	v_fma_f32 v55, -v77, v208, v55
	v_fma_f32 v55, -v75, v209, v55
	ds_read_b128 v[206:209], v5 offset:33488
	s_waitcnt lgkmcnt(8)
	v_fma_f32 v56, -v48, v228, v75
	v_fma_f32 v56, -v49, v229, v56
	v_fma_f32 v56, -v230, v50, v56
	v_fma_f32 v56, -v231, v51, v56
	ds_read_b128 v[228:231], v5 offset:33504
	s_waitcnt lgkmcnt(8)
	v_fma_f32 v56, -v178, v52, v56
	v_fma_f32 v56, -v179, v53, v56
	v_fma_f32 v56, -v180, v55, v56
	v_fma_f32 v56, -v75, v181, v56
	ds_read_b128 v[178:181], v5 offset:33728
	s_waitcnt lgkmcnt(8)
	v_fma_f32 v58, -v48, v182, v76
	v_fma_f32 v58, -v49, v183, v58
	v_fma_f32 v58, -v50, v184, v58
	v_fma_f32 v58, -v185, v51, v58
	s_waitcnt lgkmcnt(7)
	v_fma_f32 v58, -v186, v52, v58
	v_fma_f32 v58, -v187, v53, v58
	v_fma_f32 v58, -v188, v55, v58
	v_fma_f32 v58, -v189, v56, v58
	ds_read_b128 v[186:189], v5 offset:33744
	s_waitcnt lgkmcnt(7)
	v_fma_f32 v61, -v48, v190, v74
	v_fma_f32 v61, -v49, v191, v61
	v_fma_f32 v61, -v50, v192, v61
	v_fma_f32 v61, -v193, v51, v61
	ds_read_b128 v[190:193], v5 offset:33760
	s_waitcnt lgkmcnt(7)
	v_fma_f32 v61, -v194, v52, v61
	v_fma_f32 v61, -v195, v53, v61
	v_fma_f32 v61, -v196, v55, v61
	v_fma_f32 v61, -v197, v56, v61
	ds_read_b128 v[194:197], v5 offset:33984
	s_waitcnt lgkmcnt(7)
	v_fma_f32 v61, -v198, v58, v61
	v_fma_f32 v61, -v74, v199, v61
	v_fma_f32 v61, -v73, v200, v61
	v_fma_f32 v61, -v72, v201, v61
	s_waitcnt lgkmcnt(6)
	v_fma_f32 v62, -v48, v202, v73
	v_fma_f32 v62, -v49, v203, v62
	v_fma_f32 v62, -v50, v204, v62
	v_fma_f32 v62, -v51, v205, v62
	ds_read_b128 v[202:205], v5 offset:34000
	s_waitcnt lgkmcnt(6)
	v_fma_f32 v62, -v52, v206, v62
	v_fma_f32 v62, -v207, v53, v62
	v_fma_f32 v62, -v208, v55, v62
	v_fma_f32 v62, -v209, v56, v62
	ds_read_b128 v[206:209], v5 offset:34016
	s_waitcnt lgkmcnt(6)
	v_fma_f32 v62, -v228, v58, v62
	v_fma_f32 v62, -v229, v61, v62
	v_fma_f32 v62, -v73, v230, v62
	v_fma_f32 v62, -v72, v231, v62
	ds_read_b128 v[228:231], v5 offset:34240
	s_waitcnt lgkmcnt(6)
	v_fma_f32 v63, -v48, v178, v72
	v_fma_f32 v63, -v49, v179, v63
	v_fma_f32 v63, -v50, v180, v63
	v_fma_f32 v63, -v51, v181, v63
	ds_read_b128 v[178:181], v5 offset:34256
	s_waitcnt lgkmcnt(6)
	v_fma_f32 v63, -v52, v186, v63
	v_fma_f32 v63, -v187, v53, v63
	v_fma_f32 v63, -v188, v55, v63
	v_fma_f32 v63, -v189, v56, v63
	ds_read_b128 v[186:189], v5 offset:34272
	s_waitcnt lgkmcnt(6)
	v_fma_f32 v63, -v190, v58, v63
	v_fma_f32 v63, -v191, v61, v63
	v_fma_f32 v63, -v192, v62, v63
	v_fma_f32 v63, -v72, v193, v63
	s_waitcnt lgkmcnt(5)
	v_fma_f32 v70, -v48, v194, v71
	v_fma_f32 v70, -v49, v195, v70
	v_fma_f32 v70, -v50, v196, v70
	v_fma_f32 v74, -v51, v197, v70
	ds_read_b128 v[194:197], v5 offset:34288
	s_waitcnt lgkmcnt(5)
	v_fma_f32 v70, -v52, v202, v74
	v_fma_f32 v70, -v53, v203, v70
	v_fma_f32 v70, -v204, v55, v70
	v_fma_f32 v74, -v205, v56, v70
	ds_read_b128 v[202:205], v5 offset:34496
	s_waitcnt lgkmcnt(5)
	v_fma_f32 v70, -v206, v58, v74
	v_fma_f32 v70, -v207, v61, v70
	v_fma_f32 v70, -v208, v62, v70
	v_fma_f32 v70, -v209, v63, v70
	ds_read_b128 v[206:209], v5 offset:34512
	s_waitcnt lgkmcnt(5)
	v_fma_f32 v71, -v48, v228, v59
	v_fma_f32 v71, -v49, v229, v71
	v_fma_f32 v71, -v50, v230, v71
	v_fma_f32 v71, -v51, v231, v71
	ds_read_b128 v[228:231], v5 offset:34528
	s_waitcnt lgkmcnt(5)
	v_fma_f32 v71, -v52, v178, v71
	v_fma_f32 v71, -v53, v179, v71
	v_fma_f32 v71, -v55, v180, v71
	v_fma_f32 v71, -v181, v56, v71
	ds_read_b128 v[178:181], v5 offset:34544
	s_waitcnt lgkmcnt(5)
	v_fma_f32 v71, -v186, v58, v71
	v_fma_f32 v71, -v187, v61, v71
	v_fma_f32 v71, -v188, v62, v71
	v_fma_f32 v71, -v189, v63, v71
	ds_read_b128 v[186:189], v5 offset:34752
	s_waitcnt lgkmcnt(5)
	v_fma_f32 v71, -v194, v70, v71
	v_fma_f32 v59, -v59, v195, v71
	v_fma_f32 v59, -v57, v196, v59
	v_fma_f32 v59, -v54, v197, v59
	ds_read_b128 v[194:197], v5 offset:34768
	s_waitcnt lgkmcnt(5)
	v_fma_f32 v71, -v48, v202, v57
	v_fma_f32 v71, -v49, v203, v71
	v_fma_f32 v71, -v50, v204, v71
	v_fma_f32 v71, -v51, v205, v71
	ds_read_b128 v[202:205], v5 offset:34784
	s_waitcnt lgkmcnt(5)
	v_fma_f32 v71, -v52, v206, v71
	v_fma_f32 v71, -v53, v207, v71
	v_fma_f32 v71, -v55, v208, v71
	v_fma_f32 v71, -v56, v209, v71
	ds_read_b128 v[206:209], v5 offset:34800
	s_waitcnt lgkmcnt(5)
	v_fma_f32 v71, -v58, v228, v71
	v_fma_f32 v71, -v229, v61, v71
	v_fma_f32 v71, -v230, v62, v71
	v_fma_f32 v71, -v231, v63, v71
	s_waitcnt lgkmcnt(4)
	v_fma_f32 v71, -v178, v70, v71
	v_fma_f32 v71, -v179, v59, v71
	v_fma_f32 v57, -v57, v180, v71
	v_fma_f32 v57, -v54, v181, v57
	s_waitcnt lgkmcnt(3)
	v_fma_f32 v71, -v48, v186, v54
	v_fma_f32 v71, -v49, v187, v71
	v_fma_f32 v71, -v50, v188, v71
	v_fma_f32 v71, -v51, v189, v71
	s_waitcnt lgkmcnt(2)
	v_fma_f32 v71, -v52, v194, v71
	v_fma_f32 v71, -v53, v195, v71
	v_fma_f32 v71, -v55, v196, v71
	v_fma_f32 v71, -v56, v197, v71
	s_waitcnt lgkmcnt(1)
	v_fma_f32 v71, -v58, v202, v71
	v_fma_f32 v71, -v61, v203, v71
	v_fma_f32 v71, -v204, v62, v71
	v_fma_f32 v71, -v205, v63, v71
	s_waitcnt lgkmcnt(0)
	v_fma_f32 v5, -v206, v70, v71
	v_fma_f32 v5, -v207, v59, v5
	v_fma_f32 v5, -v208, v57, v5
	v_fma_f32 v5, -v54, v209, v5
	v_mov_b32_e32 v72, v206
	v_mov_b32_e32 v73, v207
	v_mov_b32_e32 v74, v208
	v_mov_b32_e32 v75, v209
	v_mov_b32_e32 v76, v192
	v_mov_b32_e32 v77, v193
	v_mov_b32_e32 v78, v200
	v_mov_b32_e32 v79, v201
	v_mov_b32_e32 v80, v184
	v_mov_b32_e32 v81, v185
	v_mov_b32_e32 v82, v214
	v_mov_b32_e32 v83, v215
	v_mov_b32_e32 v84, v216
	v_mov_b32_e32 v85, v217
	v_mov_b32_e32 v86, v244
	v_mov_b32_e32 v87, v245
	v_mov_b32_e32 v88, v246
	v_mov_b32_e32 v89, v247
	v_mov_b32_e32 v90, v232
	v_mov_b32_e32 v91, v233
	v_mov_b32_e32 v92, v234
	v_mov_b32_e32 v93, v235
	v_readlane_b32 s16, v253, 32
	v_readlane_b32 s17, v253, 33
	s_mov_b64 s[12:13], -1
	s_and_b64 vcc, exec, s[16:17]
	s_cbranch_vccz .LBB0_811
	v_add_co_u32_e32 v74, vcc, 0x4000, v68
	v_cvt_pk_bf16_f32 v54, -v60, s0
	s_mov_b64 s[12:13], 0x4000
	v_addc_co_u32_e32 v75, vcc, 0, v69, vcc
	v_lshl_add_u64 v[72:73], v[68:69], 0, s[12:13]
	global_store_short v[74:75], v54, off
	v_cvt_pk_bf16_f32 v54, -v0, s0
	global_store_short v[72:73], v54, off offset:128
	v_cvt_pk_bf16_f32 v54, -v1, s0
	global_store_short v[72:73], v54, off offset:256
	v_cvt_pk_bf16_f32 v54, -v2, s0
	global_store_short v[72:73], v54, off offset:384
	v_cvt_pk_bf16_f32 v54, -v3, s0
	global_store_short v[72:73], v54, off offset:512
	v_cvt_pk_bf16_f32 v54, -v4, s0
	global_store_short v[72:73], v54, off offset:640
	v_cvt_pk_bf16_f32 v54, -v6, s0
	global_store_short v[72:73], v54, off offset:768
	v_cvt_pk_bf16_f32 v54, -v7, s0
	global_store_short v[72:73], v54, off offset:896
	v_cvt_pk_bf16_f32 v54, -v8, s0
	global_store_short v[72:73], v54, off offset:1024
	v_cvt_pk_bf16_f32 v54, -v9, s0
	global_store_short v[72:73], v54, off offset:1152
	v_cvt_pk_bf16_f32 v54, -v10, s0
	global_store_short v[72:73], v54, off offset:1280
	v_cvt_pk_bf16_f32 v54, -v11, s0
	global_store_short v[72:73], v54, off offset:1408
	v_cvt_pk_bf16_f32 v54, -v12, s0
	global_store_short v[72:73], v54, off offset:1536
	v_cvt_pk_bf16_f32 v54, -v13, s0
	global_store_short v[72:73], v54, off offset:1664
	v_cvt_pk_bf16_f32 v54, -v14, s0
	global_store_short v[72:73], v54, off offset:1792
	v_cvt_pk_bf16_f32 v54, -v15, s0
	global_store_short v[72:73], v54, off offset:1920
	v_cvt_pk_bf16_f32 v54, -v16, s0
	global_store_short v[72:73], v54, off offset:2048
	v_cvt_pk_bf16_f32 v54, -v17, s0
	global_store_short v[72:73], v54, off offset:2176
	v_cvt_pk_bf16_f32 v54, -v18, s0
	global_store_short v[72:73], v54, off offset:2304
	v_cvt_pk_bf16_f32 v54, -v19, s0
	global_store_short v[72:73], v54, off offset:2432
	v_cvt_pk_bf16_f32 v54, -v20, s0
	global_store_short v[72:73], v54, off offset:2560
	v_cvt_pk_bf16_f32 v54, -v21, s0
	global_store_short v[72:73], v54, off offset:2688
	v_cvt_pk_bf16_f32 v54, -v22, s0
	global_store_short v[72:73], v54, off offset:2816
	v_cvt_pk_bf16_f32 v54, -v23, s0
	global_store_short v[72:73], v54, off offset:2944
	v_cvt_pk_bf16_f32 v54, -v24, s0
	global_store_short v[72:73], v54, off offset:3072
	v_cvt_pk_bf16_f32 v54, -v25, s0
	global_store_short v[72:73], v54, off offset:3200
	v_cvt_pk_bf16_f32 v54, -v26, s0
	global_store_short v[72:73], v54, off offset:3328
	v_cvt_pk_bf16_f32 v54, -v27, s0
	global_store_short v[72:73], v54, off offset:3456
	v_cvt_pk_bf16_f32 v54, -v28, s0
	global_store_short v[72:73], v54, off offset:3584
	v_cvt_pk_bf16_f32 v54, -v29, s0
	global_store_short v[72:73], v54, off offset:3712
	v_cvt_pk_bf16_f32 v54, -v30, s0
	s_movk_i32 s6, 0x5000
	global_store_short v[72:73], v54, off offset:3840
	v_cvt_pk_bf16_f32 v54, -v31, s0
	v_add_co_u32_e32 v68, vcc, s6, v68
	global_store_short v[72:73], v54, off offset:3968
	v_cvt_pk_bf16_f32 v54, -v32, s0
	v_addc_co_u32_e32 v69, vcc, 0, v69, vcc
	global_store_short v[68:69], v54, off
	v_cvt_pk_bf16_f32 v54, -v33, s0
	global_store_short v[68:69], v54, off offset:128
	v_cvt_pk_bf16_f32 v54, -v34, s0
	global_store_short v[68:69], v54, off offset:256
	v_cvt_pk_bf16_f32 v54, -v35, s0
	global_store_short v[68:69], v54, off offset:384
	v_cvt_pk_bf16_f32 v54, -v36, s0
	global_store_short v[68:69], v54, off offset:512
	v_cvt_pk_bf16_f32 v54, -v37, s0
	global_store_short v[68:69], v54, off offset:640
	v_cvt_pk_bf16_f32 v54, -v38, s0
	global_store_short v[68:69], v54, off offset:768
	v_cvt_pk_bf16_f32 v54, -v39, s0
	global_store_short v[68:69], v54, off offset:896
	v_cvt_pk_bf16_f32 v54, -v40, s0
	global_store_short v[68:69], v54, off offset:1024
	v_cvt_pk_bf16_f32 v54, -v41, s0
	global_store_short v[68:69], v54, off offset:1152
	v_cvt_pk_bf16_f32 v54, -v42, s0
	global_store_short v[68:69], v54, off offset:1280
	v_cvt_pk_bf16_f32 v54, -v43, s0
	global_store_short v[68:69], v54, off offset:1408
	v_cvt_pk_bf16_f32 v54, -v44, s0
	global_store_short v[68:69], v54, off offset:1536
	v_cvt_pk_bf16_f32 v54, -v45, s0
	global_store_short v[68:69], v54, off offset:1664
	v_cvt_pk_bf16_f32 v54, -v46, s0
	global_store_short v[68:69], v54, off offset:1792
	v_cvt_pk_bf16_f32 v54, -v47, s0
	global_store_short v[68:69], v54, off offset:1920
	v_cvt_pk_bf16_f32 v54, -v48, s0
	global_store_short v[68:69], v54, off offset:2048
	v_cvt_pk_bf16_f32 v54, -v49, s0
	global_store_short v[68:69], v54, off offset:2176
	v_cvt_pk_bf16_f32 v54, -v50, s0
	global_store_short v[68:69], v54, off offset:2304
	v_cvt_pk_bf16_f32 v54, -v51, s0
	global_store_short v[68:69], v54, off offset:2432
	v_cvt_pk_bf16_f32 v54, -v52, s0
	global_store_short v[68:69], v54, off offset:2560
	v_cvt_pk_bf16_f32 v54, -v53, s0
	global_store_short v[68:69], v54, off offset:2688
	v_cvt_pk_bf16_f32 v54, -v55, s0
	global_store_short v[68:69], v54, off offset:2816
	v_cvt_pk_bf16_f32 v54, -v56, s0
	global_store_short v[68:69], v54, off offset:2944
	v_cvt_pk_bf16_f32 v54, -v58, s0
	global_store_short v[68:69], v54, off offset:3072
	v_cvt_pk_bf16_f32 v54, -v61, s0
	global_store_short v[68:69], v54, off offset:3200
	v_cvt_pk_bf16_f32 v54, -v62, s0
	global_store_short v[68:69], v54, off offset:3328
	v_cvt_pk_bf16_f32 v54, -v63, s0
	global_store_short v[68:69], v54, off offset:3456
	v_cvt_pk_bf16_f32 v54, -v70, s0
	global_store_short v[68:69], v54, off offset:3584
	v_cvt_pk_bf16_f32 v54, -v59, s0
	global_store_short v[68:69], v54, off offset:3712
	v_cvt_pk_bf16_f32 v54, -v57, s0
	global_store_short v[68:69], v54, off offset:3840
	v_cvt_pk_bf16_f32 v54, -v5, s0
	s_mov_b64 s[12:13], 0
	global_store_short v[68:69], v54, off offset:3968
